# speedup vs baseline: 1.0957x; 1.0229x over previous
; __device__ __forceinline__ void qkt(f32x16& p0, f32x16& p1, const char* Ks, const bf16x8* qr, int r32, int hi, int map, float negM) {
; #pragma unroll
;   for (int r = 0; r < 16; ++r) { p0[r] = negM; p1[r] = negM; }
; #pragma unroll
;   for (int d0 = 0; d0 < 4; ++d0) {
;     int cb = (map * 64 + d0 * 16 + hi * 8) * 2;
;     bf16x8 b0 = *reinterpret_cast<const bf16x8*>(Ks + KSWZ(r32, cb));
;     bf16x8 b1 = *reinterpret_cast<const bf16x8*>(Ks + KSWZ(32 + r32, cb));
;     p0 = __builtin_amdgcn_mfma_f32_32x32x16_bf16(b0, qr[d0], p0, 0, 0, 0);
;     p1 = __builtin_amdgcn_mfma_f32_32x32x16_bf16(b1, qr[d0], p1, 0, 0, 0);
;   }
; template <int MODE> __device__ __forceinline__ void diff_attn_item(const bf16* __restrict__ Qb, const bf16* __restrict__ Kh, const bf16* __restrict__ Vh, ...
;     ...
;   f32x16 o[4] = {}; bf16x8 qr[4]; float lsum = 0;
;   const bf16* Qw = Qb + (long)(rb * 32 + r32) * 128 + map * 64 + hi * 8;
; #pragma unroll
;   for (int d0 = 0; d0 < 4; ++d0) qr[d0] = *reinterpret_cast<const bf16x8*>(Qw + d0 * 16);
;   const int ldsbase = (int)(uintptr_t)(__attribute__((address_space(3))) char*)lds;
;   int voff[4];
; #pragma unroll
;   for (int ks = 0; ks < 4; ++ks) voff[ks] = r32 * 128 + ((((ks << 1) | hi) ^ ((r32 >> 1) & 7)) << 4);
;   int ksrc[2], vsrc[2];
; #pragma unroll
;   for (int i = 0; i < 2; ++i) {
;     const int q = tid + i * 512;
;     const int krow = q >> 4, kc = (q & 15) ^ (krow & 15);
;     ksrc[i] = krow * 128 + kc * 8;
;     const int vrow = q >> 3, vc = (q & 7) ^ ((vrow >> 1) & 7);
;     vsrc[i] = vrow * 64 + vc * 8;
;   }
;     ...
;   const int NTL = seq / KVBLK;
;   f32x16 pc0, pc1, pn0, pn1;
;   SLOADW(0, 0);
;   SLOADW(1, KVBLK);
;   asm volatile("s_waitcnt vmcnt(0)" ::: "memory");
;   __syncthreads();
;   qkt(pc0, pc1, lds + SHM_KV, qr, r32, hi, map, negM);
;   int s_cur = 0, s_nxt = 1, s_wr = 2;
;   for (int j = 0; j < NTL; ++j) {
;     const bool has1 = (j + 1 < NTL), has2 = (j + 2 < NTL);
;     if (has2 && MODE == 0) SLOADW(s_wr, (j + 2) * KVBLK);
;     bf16x8 f0, f1, f2, f3;
;     if (has1) qkt(pn0, pn1, lds + s_nxt * SHM_BUF + SHM_KV, qr, r32, hi, map, negM);
.Lda0_new:
	v_and_b32_e32 v250, 31, v163
	v_bfe_u32 v251, v163, 5, 1
	v_lshrrev_b32_e32 v252, 8, v163
	v_and_b32_e32 v248, 15, v250
	v_lshlrev_b32_e32 v248, 4, v248
	v_lshlrev_b32_e32 v249, 7, v252
	v_lshl_or_b32 v249, v251, 4, v249
	v_xor_b32_e32 v248, v248, v249
	v_lshl_or_b32 v228, v250, 8, v248
	v_add_u32_e32 v228, 0xc000, v228
	v_xor_b32_e32 v229, 32, v228
	v_xor_b32_e32 v230, 64, v228
	v_xor_b32_e32 v231, 96, v228
	v_bfe_u32 v248, v250, 1, 3
	v_xor_b32_e32 v248, v248, v251
	v_lshlrev_b32_e32 v248, 4, v248
	v_lshl_or_b32 v232, v250, 7, v248
	v_xor_b32_e32 v233, 32, v232
	v_xor_b32_e32 v234, 64, v232
	v_xor_b32_e32 v235, 96, v232
	v_lshrrev_b32_e32 v248, 4, v163
	v_xor_b32_e32 v249, v248, v163
	v_and_b32_e32 v249, 15, v249
	v_lshlrev_b32_e32 v249, 4, v249
	v_lshl_or_b32 v236, v248, 8, v249
	v_add_u32_e32 v237, 0x2000, v236
	v_xor_b32_e32 v249, v248, v163
	v_and_b32_e32 v249, 7, v249
	v_lshlrev_b32_e32 v249, 4, v249
	v_lshrrev_b32_e32 v248, 3, v163
	v_lshl_or_b32 v246, v248, 7, v249
	v_add_u32_e32 v247, 0x2000, v246
	v_lshrrev_b32_e32 v248, 6, v163
	v_lshlrev_b32_e32 v248, 10, v248
	v_mov_b32_e32 v190, 0
	v_mov_b32_e32 v191, 0
	v_mov_b32_e32 v66, 0
	v_mov_b32_e32 v67, 0
	v_mov_b32_e32 v68, 0
	v_mov_b32_e32 v69, 0
	v_mov_b32_e32 v70, 0
	v_mov_b32_e32 v71, 0
	v_mov_b32_e32 v72, 0
	v_mov_b32_e32 v73, 0
	v_mov_b32_e32 v74, 0
	v_mov_b32_e32 v75, 0
	v_mov_b32_e32 v76, 0
	v_mov_b32_e32 v77, 0
	v_mov_b32_e32 v78, 0
	v_mov_b32_e32 v79, 0
	v_mov_b32_e32 v80, 0
	v_mov_b32_e32 v81, 0
	v_mov_b32_e32 v50, 0
	v_mov_b32_e32 v51, 0
	v_mov_b32_e32 v52, 0
	v_mov_b32_e32 v53, 0
	v_mov_b32_e32 v54, 0
	v_mov_b32_e32 v55, 0
	v_mov_b32_e32 v56, 0
	v_mov_b32_e32 v57, 0
	v_mov_b32_e32 v58, 0
	v_mov_b32_e32 v59, 0
	v_mov_b32_e32 v60, 0
	v_mov_b32_e32 v61, 0
	v_mov_b32_e32 v62, 0
	v_mov_b32_e32 v63, 0
	v_mov_b32_e32 v64, 0
	v_mov_b32_e32 v65, 0
	v_mov_b32_e32 v34, 0
	v_mov_b32_e32 v35, 0
	v_mov_b32_e32 v36, 0
	v_mov_b32_e32 v37, 0
	v_mov_b32_e32 v38, 0
	v_mov_b32_e32 v39, 0
	v_mov_b32_e32 v40, 0
	v_mov_b32_e32 v41, 0
	v_mov_b32_e32 v42, 0
	v_mov_b32_e32 v43, 0
	v_mov_b32_e32 v44, 0
	v_mov_b32_e32 v45, 0
	v_mov_b32_e32 v46, 0
	v_mov_b32_e32 v47, 0
	v_mov_b32_e32 v48, 0
	v_mov_b32_e32 v49, 0
	v_mov_b32_e32 v18, 0
	v_mov_b32_e32 v19, 0
	v_mov_b32_e32 v20, 0
	v_mov_b32_e32 v21, 0
	v_mov_b32_e32 v22, 0
	v_mov_b32_e32 v23, 0
	v_mov_b32_e32 v24, 0
	v_mov_b32_e32 v25, 0
	v_mov_b32_e32 v26, 0
	v_mov_b32_e32 v27, 0
	v_mov_b32_e32 v28, 0
	v_mov_b32_e32 v29, 0
	v_mov_b32_e32 v30, 0
	v_mov_b32_e32 v31, 0
	v_mov_b32_e32 v32, 0
	v_mov_b32_e32 v33, 0
	v_readfirstlane_b32 s14, v248
	s_waitcnt lgkmcnt(0)
	s_nop 3
	s_add_u32 m0, s14, 0xc000
	s_nop 0
	global_load_lds_dwordx4 v236, s[8:9]
	s_add_u32 m0, s14, 0xe000
	s_nop 0
	global_load_lds_dwordx4 v237, s[8:9]
	s_add_u32 s8, s8, 0x4000
	s_addc_u32 s9, s9, 0
	s_add_u32 m0, s14, 0x10000
	s_nop 0
	global_load_lds_dwordx4 v236, s[8:9]
	s_add_u32 m0, s14, 0x12000
	s_nop 0
	global_load_lds_dwordx4 v237, s[8:9]
	s_add_u32 s8, s8, 0x4000
	s_addc_u32 s9, s9, 0
	s_add_u32 m0, s14, 0x14000
	s_nop 0
	global_load_lds_dwordx4 v236, s[8:9]
	s_add_u32 m0, s14, 0x16000
	s_nop 0
	global_load_lds_dwordx4 v237, s[8:9]
	s_add_u32 s8, s8, 0x4000
	s_addc_u32 s9, s9, 0
	s_mov_b32 m0, s14
	s_nop 0
	global_load_lds_dwordx4 v246, s[10:11]
	s_add_u32 m0, s14, 0x2000
	s_nop 0
	global_load_lds_dwordx4 v247, s[10:11]
	s_add_u32 s10, s10, 0x4000
	s_addc_u32 s11, s11, 0
	s_waitcnt vmcnt(0)
	s_barrier
	ds_read_b128 v[186:189], v228 offset:0
	ds_read_b128 v[200:203], v229 offset:0
	ds_read_b128 v[204:207], v230 offset:0
	ds_read_b128 v[208:211], v231 offset:0
	ds_read_b128 v[212:215], v228 offset:8192
	ds_read_b128 v[216:219], v229 offset:8192
	ds_read_b128 v[220:223], v230 offset:8192
	ds_read_b128 v[224:227], v231 offset:8192
	s_waitcnt lgkmcnt(7)
	v_mfma_f32_32x32x16_bf16 v[82:97], v[186:189], v[158:161], v[0:15]
	s_waitcnt lgkmcnt(6)
	v_mfma_f32_32x32x16_bf16 v[82:97], v[200:203], v[154:157], v[82:97]
	s_waitcnt lgkmcnt(5)
	v_mfma_f32_32x32x16_bf16 v[82:97], v[204:207], v[150:153], v[82:97]
	s_waitcnt lgkmcnt(4)
	v_mfma_f32_32x32x16_bf16 v[82:97], v[208:211], v[146:149], v[82:97]
	s_waitcnt lgkmcnt(3)
	v_mfma_f32_32x32x16_bf16 v[98:113], v[212:215], v[158:161], v[0:15]
	s_waitcnt lgkmcnt(2)
	v_mfma_f32_32x32x16_bf16 v[98:113], v[216:219], v[154:157], v[98:113]
	s_waitcnt lgkmcnt(1)
	v_mfma_f32_32x32x16_bf16 v[98:113], v[220:223], v[150:153], v[98:113]
	s_waitcnt lgkmcnt(0)
	v_mfma_f32_32x32x16_bf16 v[98:113], v[224:227], v[146:149], v[98:113]
	s_barrier
; template <int MODE> __device__ __forceinline__ void sm_half(f32x16& p, float& lsum, bf16x8& f0, bf16x8& f1) {
;   if (MODE != 3) {
; #pragma unroll
;   for (int r = 0; r < 16; ++r) p[r] = __builtin_amdgcn_exp2f(p[r]);
;   }
;   float s0 = 0, s1 = 0;
; #pragma unroll
;   for (int r = 0; r < 16; r += 2) { s0 += p[r]; s1 += p[r + 1]; }
;   lsum += s0 + s1;
;   u32x4 w0 = {cvtpk(p[0], p[1]), cvtpk(p[2], p[3]), cvtpk(p[4], p[5]), cvtpk(p[6], p[7])};
;   u32x4 w1 = {cvtpk(p[8], p[9]), cvtpk(p[10], p[11]), cvtpk(p[12], p[13]), cvtpk(p[14], p[15])};
;   f0 = *reinterpret_cast<bf16x8*>(&w0); f1 = *reinterpret_cast<bf16x8*>(&w1);
; }
; template <int MODE> __device__ __forceinline__ void diff_attn_item(const bf16* __restrict__ Qb, const bf16* __restrict__ Kh, const bf16* __restrict__ Vh, ...
;     ...
;   for (int j = 0; j < NTL; ++j) {
;     const bool has1 = (j + 1 < NTL), has2 = (j + 2 < NTL);
;     if (has2 && MODE == 0) SLOADW(s_wr, (j + 2) * KVBLK);
;     bf16x8 f0, f1, f2, f3;
;     if (has1) qkt(pn0, pn1, lds + s_nxt * SHM_BUF + SHM_KV, qr, r32, hi, map, negM);
;     sm_half<MODE>(pc0, lsum, f0, f1);
;     const char* vt = lds + s_cur * SHM_BUF;
;     pv_b128(o, vt + voff[0], f0); pv_b128(o, vt + voff[1], f1);
;     sm_half<MODE>(pc1, lsum, f2, f3);
;     pv_b128(o, vt + voff[2], f2); pv_b128(o, vt + voff[3], f3);
	s_add_u32 m0, s14, 0x4000
	s_nop 0
	global_load_lds_dwordx4 v246, s[10:11]
	s_add_u32 m0, s14, 0x6000
	s_nop 0
	global_load_lds_dwordx4 v247, s[10:11]
	s_add_u32 s10, s10, 0x4000
	s_addc_u32 s11, s11, 0
	s_add_u32 m0, s14, 0xc000
	s_nop 0
	global_load_lds_dwordx4 v236, s[8:9]
	s_add_u32 m0, s14, 0xe000
	s_nop 0
	global_load_lds_dwordx4 v237, s[8:9]
	s_add_u32 s8, s8, 0x4000
	s_addc_u32 s9, s9, 0
	ds_read_b128 v[186:189], v228 offset:16384
	ds_read_b128 v[200:203], v229 offset:16384
	ds_read_b128 v[204:207], v230 offset:16384
	ds_read_b128 v[208:211], v231 offset:16384
	ds_read_b128 v[212:215], v228 offset:24576
	ds_read_b128 v[216:219], v229 offset:24576
	ds_read_b128 v[220:223], v230 offset:24576
	ds_read_b128 v[224:227], v231 offset:24576
	v_exp_f32_e32 v130, v82
	v_exp_f32_e32 v131, v83
	v_add_f32_e32 v190, v190, v130
	v_exp_f32_e32 v132, v84
	v_exp_f32_e32 v133, v85
	v_add_f32_e32 v191, v191, v131
	v_exp_f32_e32 v134, v86
	v_exp_f32_e32 v135, v87
	v_add_f32_e32 v190, v190, v132
	v_exp_f32_e32 v136, v88
	v_exp_f32_e32 v137, v89
	v_add_f32_e32 v191, v191, v133
	v_exp_f32_e32 v138, v90
	v_exp_f32_e32 v139, v91
	v_cvt_pk_bf16_f32 v114, v130, v131
	v_exp_f32_e32 v140, v92
	v_exp_f32_e32 v141, v93
	v_cvt_pk_bf16_f32 v115, v132, v133
	v_exp_f32_e32 v142, v94
	v_exp_f32_e32 v143, v95
	v_add_f32_e32 v190, v190, v134
	v_exp_f32_e32 v144, v96
	v_exp_f32_e32 v145, v97
	v_add_f32_e32 v191, v191, v135
	v_exp_f32_e32 v238, v98
	v_exp_f32_e32 v239, v99
	v_cvt_pk_bf16_f32 v116, v134, v135
	v_exp_f32_e32 v240, v100
	v_exp_f32_e32 v241, v101
	v_add_f32_e32 v190, v190, v136
	v_exp_f32_e32 v242, v102
	v_exp_f32_e32 v243, v103
	v_add_f32_e32 v191, v191, v137
	v_exp_f32_e32 v244, v104
	v_exp_f32_e32 v245, v105
	v_cvt_pk_bf16_f32 v117, v136, v137
	v_exp_f32_e32 v130, v106
	v_exp_f32_e32 v131, v107
	v_add_f32_e32 v190, v190, v138
	v_exp_f32_e32 v132, v108
	v_exp_f32_e32 v133, v109
	v_add_f32_e32 v191, v191, v139
	v_exp_f32_e32 v134, v110
	v_exp_f32_e32 v135, v111
	v_add_f32_e32 v190, v190, v140
	v_exp_f32_e32 v136, v112
	v_exp_f32_e32 v137, v113
	v_add_f32_e32 v191, v191, v141
	s_waitcnt lgkmcnt(7)
	v_mfma_f32_32x32x16_bf16 v[82:97], v[186:189], v[158:161], v[0:15]
	ds_read_b128 v[166:169], v232 offset:0
	v_cvt_pk_bf16_f32 v118, v138, v139
	v_cvt_pk_bf16_f32 v119, v140, v141
	v_add_f32_e32 v190, v190, v142
	v_add_f32_e32 v191, v191, v143
	s_waitcnt lgkmcnt(7)
	v_mfma_f32_32x32x16_bf16 v[82:97], v[200:203], v[154:157], v[82:97]
	ds_read_b128 v[170:173], v232 offset:4096
	v_cvt_pk_bf16_f32 v120, v142, v143
	v_add_f32_e32 v190, v190, v144
	v_add_f32_e32 v191, v191, v145
	v_cvt_pk_bf16_f32 v121, v144, v145
	s_waitcnt lgkmcnt(7)
	v_mfma_f32_32x32x16_bf16 v[82:97], v[204:207], v[150:153], v[82:97]
	ds_read_b128 v[178:181], v232 offset:8192
	v_add_f32_e32 v190, v190, v238
	v_add_f32_e32 v191, v191, v239
	v_cvt_pk_bf16_f32 v122, v238, v239
	v_add_f32_e32 v190, v190, v240
	s_waitcnt lgkmcnt(7)
	v_mfma_f32_32x32x16_bf16 v[82:97], v[208:211], v[146:149], v[82:97]
	ds_read_b128 v[182:185], v232 offset:12288
	v_add_f32_e32 v191, v191, v241
	v_cvt_pk_bf16_f32 v123, v240, v241
	v_add_f32_e32 v190, v190, v242
	v_add_f32_e32 v191, v191, v243
	s_waitcnt lgkmcnt(7)
	v_mfma_f32_32x32x16_bf16 v[98:113], v[212:215], v[158:161], v[0:15]
	ds_read_b128 v[186:189], v233 offset:0
	v_cvt_pk_bf16_f32 v124, v242, v243
	v_add_f32_e32 v190, v190, v244
	v_add_f32_e32 v191, v191, v245
	v_cvt_pk_bf16_f32 v125, v244, v245
	s_waitcnt lgkmcnt(7)
	v_mfma_f32_32x32x16_bf16 v[98:113], v[216:219], v[154:157], v[98:113]
	ds_read_b128 v[200:203], v233 offset:4096
	v_add_f32_e32 v190, v190, v130
	v_add_f32_e32 v191, v191, v131
	v_cvt_pk_bf16_f32 v126, v130, v131
	v_add_f32_e32 v190, v190, v132
	s_waitcnt lgkmcnt(7)
	v_mfma_f32_32x32x16_bf16 v[98:113], v[220:223], v[150:153], v[98:113]
	ds_read_b128 v[204:207], v233 offset:8192
	v_add_f32_e32 v191, v191, v133
	v_cvt_pk_bf16_f32 v127, v132, v133
	v_add_f32_e32 v190, v190, v134
	v_add_f32_e32 v191, v191, v135
	s_waitcnt lgkmcnt(7)
	v_mfma_f32_32x32x16_bf16 v[98:113], v[224:227], v[146:149], v[98:113]
	ds_read_b128 v[208:211], v233 offset:12288
	v_cvt_pk_bf16_f32 v128, v134, v135
	v_add_f32_e32 v190, v190, v136
	v_add_f32_e32 v191, v191, v137
	v_cvt_pk_bf16_f32 v129, v136, v137
	s_waitcnt vmcnt(2)
	s_movk_i32 s15, 42
; template <int MODE> __device__ __forceinline__ void diff_attn_item(const bf16* __restrict__ Qb, const bf16* __restrict__ Kh, const bf16* __restrict__ Vh, ...
;     ...
;   for (int j = 0; j < NTL; ++j) {
;     const bool has1 = (j + 1 < NTL), has2 = (j + 2 < NTL);
;     if (has2 && MODE == 0) SLOADW(s_wr, (j + 2) * KVBLK);
;     bf16x8 f0, f1, f2, f3;
;     if (has1) qkt(pn0, pn1, lds + s_nxt * SHM_BUF + SHM_KV, qr, r32, hi, map, negM);
;     sm_half<MODE>(pc0, lsum, f0, f1);
;     const char* vt = lds + s_cur * SHM_BUF;
;     pv_b128(o, vt + voff[0], f0); pv_b128(o, vt + voff[1], f1);
;     sm_half<MODE>(pc1, lsum, f2, f3);
;     pv_b128(o, vt + voff[2], f2); pv_b128(o, vt + voff[3], f3);
;     asm volatile("s_waitcnt vmcnt(0)" ::: "memory");
;     __syncthreads();
;     pc0 = pn0; pc1 = pn1;
;     const int t = s_cur; s_cur = s_nxt; s_nxt = s_wr; s_wr = t;
.Lda0_loop:
	s_barrier
	s_waitcnt lgkmcnt(7)
	v_mfma_f32_32x32x16_bf16 v[66:81], v[166:169], v[114:117], v[66:81]
	s_add_u32 m0, s14, 0x8000
	ds_read_b128 v[212:215], v234 offset:0
	global_load_lds_dwordx4 v246, s[10:11]
	v_exp_f32_e32 v130, v82
	v_exp_f32_e32 v131, v83
	v_add_f32_e32 v190, v190, v130
	s_waitcnt lgkmcnt(7)
	v_mfma_f32_32x32x16_bf16 v[50:65], v[170:173], v[114:117], v[50:65]
	s_add_u32 m0, s14, 0xa000
	ds_read_b128 v[216:219], v234 offset:4096
	global_load_lds_dwordx4 v247, s[10:11]
	s_add_u32 s10, s10, 0x4000
	s_addc_u32 s11, s11, 0
	v_exp_f32_e32 v132, v84
	v_exp_f32_e32 v133, v85
	v_add_f32_e32 v191, v191, v131
	s_waitcnt lgkmcnt(7)
	v_mfma_f32_32x32x16_bf16 v[34:49], v[178:181], v[114:117], v[34:49]
	s_add_u32 m0, s14, 0x10000
	ds_read_b128 v[220:223], v234 offset:8192
	global_load_lds_dwordx4 v236, s[8:9]
	v_exp_f32_e32 v134, v86
	v_exp_f32_e32 v135, v87
	v_add_f32_e32 v190, v190, v132
	s_waitcnt lgkmcnt(7)
	v_mfma_f32_32x32x16_bf16 v[18:33], v[182:185], v[114:117], v[18:33]
	s_add_u32 m0, s14, 0x12000
	ds_read_b128 v[224:227], v234 offset:12288
	global_load_lds_dwordx4 v237, s[8:9]
	s_add_u32 s8, s8, 0x4000
	s_addc_u32 s9, s9, 0
	v_exp_f32_e32 v136, v88
	v_exp_f32_e32 v137, v89
	v_add_f32_e32 v191, v191, v133
	s_waitcnt lgkmcnt(7)
	v_mfma_f32_32x32x16_bf16 v[66:81], v[186:189], v[118:121], v[66:81]
	ds_read_b128 v[166:169], v235 offset:0
	v_exp_f32_e32 v138, v90
	v_exp_f32_e32 v139, v91
	v_cvt_pk_bf16_f32 v114, v130, v131
	s_waitcnt lgkmcnt(7)
	v_mfma_f32_32x32x16_bf16 v[50:65], v[200:203], v[118:121], v[50:65]
	ds_read_b128 v[170:173], v235 offset:4096
	v_exp_f32_e32 v140, v92
	v_exp_f32_e32 v141, v93
	v_cvt_pk_bf16_f32 v115, v132, v133
	s_waitcnt lgkmcnt(7)
	v_mfma_f32_32x32x16_bf16 v[34:49], v[204:207], v[118:121], v[34:49]
	ds_read_b128 v[178:181], v235 offset:8192
	v_exp_f32_e32 v142, v94
	v_exp_f32_e32 v143, v95
	v_add_f32_e32 v190, v190, v134
	s_waitcnt lgkmcnt(7)
	v_mfma_f32_32x32x16_bf16 v[18:33], v[208:211], v[118:121], v[18:33]
	ds_read_b128 v[182:185], v235 offset:12288
	v_exp_f32_e32 v144, v96
	v_exp_f32_e32 v145, v97
	v_add_f32_e32 v191, v191, v135
	s_waitcnt lgkmcnt(7)
	v_mfma_f32_32x32x16_bf16 v[66:81], v[212:215], v[122:125], v[66:81]
	ds_read_b128 v[186:189], v228 offset:32768
	v_exp_f32_e32 v238, v98
	v_exp_f32_e32 v239, v99
	v_cvt_pk_bf16_f32 v116, v134, v135
	s_waitcnt lgkmcnt(7)
	v_mfma_f32_32x32x16_bf16 v[50:65], v[216:219], v[122:125], v[50:65]
	ds_read_b128 v[200:203], v229 offset:32768
	v_exp_f32_e32 v240, v100
	v_exp_f32_e32 v241, v101
	v_add_f32_e32 v190, v190, v136
	s_waitcnt lgkmcnt(7)
	v_mfma_f32_32x32x16_bf16 v[34:49], v[220:223], v[122:125], v[34:49]
	ds_read_b128 v[204:207], v230 offset:32768
	v_exp_f32_e32 v242, v102
	v_exp_f32_e32 v243, v103
	v_add_f32_e32 v191, v191, v137
	s_waitcnt lgkmcnt(7)
	v_mfma_f32_32x32x16_bf16 v[18:33], v[224:227], v[122:125], v[18:33]
	ds_read_b128 v[208:211], v231 offset:32768
	v_exp_f32_e32 v244, v104
	v_exp_f32_e32 v245, v105
	v_cvt_pk_bf16_f32 v117, v136, v137
	s_waitcnt lgkmcnt(7)
	v_mfma_f32_32x32x16_bf16 v[66:81], v[166:169], v[126:129], v[66:81]
	ds_read_b128 v[212:215], v228 offset:40960
	v_exp_f32_e32 v130, v106
	v_exp_f32_e32 v131, v107
	v_add_f32_e32 v190, v190, v138
	s_waitcnt lgkmcnt(7)
	v_mfma_f32_32x32x16_bf16 v[50:65], v[170:173], v[126:129], v[50:65]
	ds_read_b128 v[216:219], v229 offset:40960
	v_exp_f32_e32 v132, v108
	v_exp_f32_e32 v133, v109
	v_add_f32_e32 v191, v191, v139
	s_waitcnt lgkmcnt(7)
	v_mfma_f32_32x32x16_bf16 v[34:49], v[178:181], v[126:129], v[34:49]
	ds_read_b128 v[220:223], v230 offset:40960
	v_exp_f32_e32 v134, v110
	v_exp_f32_e32 v135, v111
	v_add_f32_e32 v190, v190, v140
	s_waitcnt lgkmcnt(7)
	v_mfma_f32_32x32x16_bf16 v[18:33], v[182:185], v[126:129], v[18:33]
	ds_read_b128 v[224:227], v231 offset:40960
	v_exp_f32_e32 v136, v112
	v_exp_f32_e32 v137, v113
	v_add_f32_e32 v191, v191, v141
	s_waitcnt lgkmcnt(7)
	v_mfma_f32_32x32x16_bf16 v[82:97], v[186:189], v[158:161], v[0:15]
	ds_read_b128 v[166:169], v232 offset:16384
	v_cvt_pk_bf16_f32 v118, v138, v139
	v_cvt_pk_bf16_f32 v119, v140, v141
	v_add_f32_e32 v190, v190, v142
	v_add_f32_e32 v191, v191, v143
	s_waitcnt lgkmcnt(7)
	v_mfma_f32_32x32x16_bf16 v[82:97], v[200:203], v[154:157], v[82:97]
	ds_read_b128 v[170:173], v232 offset:20480
	v_cvt_pk_bf16_f32 v120, v142, v143
	v_add_f32_e32 v190, v190, v144
	v_add_f32_e32 v191, v191, v145
	v_cvt_pk_bf16_f32 v121, v144, v145
	s_waitcnt lgkmcnt(7)
	v_mfma_f32_32x32x16_bf16 v[82:97], v[204:207], v[150:153], v[82:97]
	ds_read_b128 v[178:181], v232 offset:24576
	v_add_f32_e32 v190, v190, v238
	v_add_f32_e32 v191, v191, v239
	v_cvt_pk_bf16_f32 v122, v238, v239
	v_add_f32_e32 v190, v190, v240
	s_waitcnt lgkmcnt(7)
	v_mfma_f32_32x32x16_bf16 v[82:97], v[208:211], v[146:149], v[82:97]
	ds_read_b128 v[182:185], v232 offset:28672
	v_add_f32_e32 v191, v191, v241
	v_cvt_pk_bf16_f32 v123, v240, v241
	v_add_f32_e32 v190, v190, v242
	v_add_f32_e32 v191, v191, v243
	s_waitcnt lgkmcnt(7)
	v_mfma_f32_32x32x16_bf16 v[98:113], v[212:215], v[158:161], v[0:15]
	ds_read_b128 v[186:189], v233 offset:16384
	v_cvt_pk_bf16_f32 v124, v242, v243
	v_add_f32_e32 v190, v190, v244
	v_add_f32_e32 v191, v191, v245
	v_cvt_pk_bf16_f32 v125, v244, v245
	s_waitcnt lgkmcnt(7)
	v_mfma_f32_32x32x16_bf16 v[98:113], v[216:219], v[154:157], v[98:113]
	ds_read_b128 v[200:203], v233 offset:20480
	v_add_f32_e32 v190, v190, v130
	v_add_f32_e32 v191, v191, v131
	v_cvt_pk_bf16_f32 v126, v130, v131
	v_add_f32_e32 v190, v190, v132
	s_waitcnt lgkmcnt(7)
	v_mfma_f32_32x32x16_bf16 v[98:113], v[220:223], v[150:153], v[98:113]
	ds_read_b128 v[204:207], v233 offset:24576
	v_add_f32_e32 v191, v191, v133
	v_cvt_pk_bf16_f32 v127, v132, v133
	v_add_f32_e32 v190, v190, v134
	v_add_f32_e32 v191, v191, v135
	s_waitcnt lgkmcnt(7)
	v_mfma_f32_32x32x16_bf16 v[98:113], v[224:227], v[146:149], v[98:113]
	ds_read_b128 v[208:211], v233 offset:28672
	v_cvt_pk_bf16_f32 v128, v134, v135
	v_add_f32_e32 v190, v190, v136
	v_add_f32_e32 v191, v191, v137
	v_cvt_pk_bf16_f32 v129, v136, v137
	s_waitcnt vmcnt(2)
	s_barrier
; template <int MODE> __device__ __forceinline__ void diff_attn_item(const bf16* __restrict__ Qb, const bf16* __restrict__ Kh, const bf16* __restrict__ Vh, ...
;     ...
;   for (int j = 0; j < NTL; ++j) {
;     const bool has1 = (j + 1 < NTL), has2 = (j + 2 < NTL);
;     if (has2 && MODE == 0) SLOADW(s_wr, (j + 2) * KVBLK);
;     bf16x8 f0, f1, f2, f3;
;     if (has1) qkt(pn0, pn1, lds + s_nxt * SHM_BUF + SHM_KV, qr, r32, hi, map, negM);
;     sm_half<MODE>(pc0, lsum, f0, f1);
;     const char* vt = lds + s_cur * SHM_BUF;
;     pv_b128(o, vt + voff[0], f0); pv_b128(o, vt + voff[1], f1);
;     sm_half<MODE>(pc1, lsum, f2, f3);
;     pv_b128(o, vt + voff[2], f2); pv_b128(o, vt + voff[3], f3);
;     asm volatile("s_waitcnt vmcnt(0)" ::: "memory");
;     __syncthreads();
;     pc0 = pn0; pc1 = pn1;
;     const int t = s_cur; s_cur = s_nxt; s_nxt = s_wr; s_wr = t;
	s_waitcnt lgkmcnt(7)
	v_mfma_f32_32x32x16_bf16 v[66:81], v[166:169], v[114:117], v[66:81]
	s_mov_b32 m0, s14
	ds_read_b128 v[212:215], v234 offset:16384
	global_load_lds_dwordx4 v246, s[10:11]
	v_exp_f32_e32 v130, v82
	v_exp_f32_e32 v131, v83
	v_add_f32_e32 v190, v190, v130
	s_waitcnt lgkmcnt(7)
	v_mfma_f32_32x32x16_bf16 v[50:65], v[170:173], v[114:117], v[50:65]
	s_add_u32 m0, s14, 0x2000
	ds_read_b128 v[216:219], v234 offset:20480
	global_load_lds_dwordx4 v247, s[10:11]
	s_add_u32 s10, s10, 0x4000
	s_addc_u32 s11, s11, 0
	v_exp_f32_e32 v132, v84
	v_exp_f32_e32 v133, v85
	v_add_f32_e32 v191, v191, v131
	s_waitcnt lgkmcnt(7)
	v_mfma_f32_32x32x16_bf16 v[34:49], v[178:181], v[114:117], v[34:49]
	s_add_u32 m0, s14, 0x14000
	ds_read_b128 v[220:223], v234 offset:24576
	global_load_lds_dwordx4 v236, s[8:9]
	v_exp_f32_e32 v134, v86
	v_exp_f32_e32 v135, v87
	v_add_f32_e32 v190, v190, v132
	s_waitcnt lgkmcnt(7)
	v_mfma_f32_32x32x16_bf16 v[18:33], v[182:185], v[114:117], v[18:33]
	s_add_u32 m0, s14, 0x16000
	ds_read_b128 v[224:227], v234 offset:28672
	global_load_lds_dwordx4 v237, s[8:9]
	s_add_u32 s8, s8, 0x4000
	s_addc_u32 s9, s9, 0
	v_exp_f32_e32 v136, v88
	v_exp_f32_e32 v137, v89
	v_add_f32_e32 v191, v191, v133
	s_waitcnt lgkmcnt(7)
	v_mfma_f32_32x32x16_bf16 v[66:81], v[186:189], v[118:121], v[66:81]
	ds_read_b128 v[166:169], v235 offset:16384
	v_exp_f32_e32 v138, v90
	v_exp_f32_e32 v139, v91
	v_cvt_pk_bf16_f32 v114, v130, v131
	s_waitcnt lgkmcnt(7)
	v_mfma_f32_32x32x16_bf16 v[50:65], v[200:203], v[118:121], v[50:65]
	ds_read_b128 v[170:173], v235 offset:20480
	v_exp_f32_e32 v140, v92
	v_exp_f32_e32 v141, v93
	v_cvt_pk_bf16_f32 v115, v132, v133
	s_waitcnt lgkmcnt(7)
	v_mfma_f32_32x32x16_bf16 v[34:49], v[204:207], v[118:121], v[34:49]
	ds_read_b128 v[178:181], v235 offset:24576
	v_exp_f32_e32 v142, v94
	v_exp_f32_e32 v143, v95
	v_add_f32_e32 v190, v190, v134
	s_waitcnt lgkmcnt(7)
	v_mfma_f32_32x32x16_bf16 v[18:33], v[208:211], v[118:121], v[18:33]
	ds_read_b128 v[182:185], v235 offset:28672
	v_exp_f32_e32 v144, v96
	v_exp_f32_e32 v145, v97
	v_add_f32_e32 v191, v191, v135
	s_waitcnt lgkmcnt(7)
	v_mfma_f32_32x32x16_bf16 v[66:81], v[212:215], v[122:125], v[66:81]
	ds_read_b128 v[186:189], v228 offset:0
	v_exp_f32_e32 v238, v98
	v_exp_f32_e32 v239, v99
	v_cvt_pk_bf16_f32 v116, v134, v135
	s_waitcnt lgkmcnt(7)
	v_mfma_f32_32x32x16_bf16 v[50:65], v[216:219], v[122:125], v[50:65]
	ds_read_b128 v[200:203], v229 offset:0
	v_exp_f32_e32 v240, v100
	v_exp_f32_e32 v241, v101
	v_add_f32_e32 v190, v190, v136
	s_waitcnt lgkmcnt(7)
	v_mfma_f32_32x32x16_bf16 v[34:49], v[220:223], v[122:125], v[34:49]
	ds_read_b128 v[204:207], v230 offset:0
	v_exp_f32_e32 v242, v102
	v_exp_f32_e32 v243, v103
	v_add_f32_e32 v191, v191, v137
	s_waitcnt lgkmcnt(7)
	v_mfma_f32_32x32x16_bf16 v[18:33], v[224:227], v[122:125], v[18:33]
	ds_read_b128 v[208:211], v231 offset:0
	v_exp_f32_e32 v244, v104
	v_exp_f32_e32 v245, v105
	v_cvt_pk_bf16_f32 v117, v136, v137
	s_waitcnt lgkmcnt(7)
	v_mfma_f32_32x32x16_bf16 v[66:81], v[166:169], v[126:129], v[66:81]
	ds_read_b128 v[212:215], v228 offset:8192
	v_exp_f32_e32 v130, v106
	v_exp_f32_e32 v131, v107
	v_add_f32_e32 v190, v190, v138
	s_waitcnt lgkmcnt(7)
	v_mfma_f32_32x32x16_bf16 v[50:65], v[170:173], v[126:129], v[50:65]
	ds_read_b128 v[216:219], v229 offset:8192
	v_exp_f32_e32 v132, v108
	v_exp_f32_e32 v133, v109
	v_add_f32_e32 v191, v191, v139
	s_waitcnt lgkmcnt(7)
	v_mfma_f32_32x32x16_bf16 v[34:49], v[178:181], v[126:129], v[34:49]
	ds_read_b128 v[220:223], v230 offset:8192
	v_exp_f32_e32 v134, v110
	v_exp_f32_e32 v135, v111
	v_add_f32_e32 v190, v190, v140
	s_waitcnt lgkmcnt(7)
	v_mfma_f32_32x32x16_bf16 v[18:33], v[182:185], v[126:129], v[18:33]
	ds_read_b128 v[224:227], v231 offset:8192
	v_exp_f32_e32 v136, v112
	v_exp_f32_e32 v137, v113
	v_add_f32_e32 v191, v191, v141
	s_waitcnt lgkmcnt(7)
	v_mfma_f32_32x32x16_bf16 v[82:97], v[186:189], v[158:161], v[0:15]
	ds_read_b128 v[166:169], v232 offset:32768
	v_cvt_pk_bf16_f32 v118, v138, v139
	v_cvt_pk_bf16_f32 v119, v140, v141
	v_add_f32_e32 v190, v190, v142
	v_add_f32_e32 v191, v191, v143
	s_waitcnt lgkmcnt(7)
	v_mfma_f32_32x32x16_bf16 v[82:97], v[200:203], v[154:157], v[82:97]
	ds_read_b128 v[170:173], v232 offset:36864
	v_cvt_pk_bf16_f32 v120, v142, v143
	v_add_f32_e32 v190, v190, v144
	v_add_f32_e32 v191, v191, v145
	v_cvt_pk_bf16_f32 v121, v144, v145
	s_waitcnt lgkmcnt(7)
	v_mfma_f32_32x32x16_bf16 v[82:97], v[204:207], v[150:153], v[82:97]
	ds_read_b128 v[178:181], v232 offset:40960
	v_add_f32_e32 v190, v190, v238
	v_add_f32_e32 v191, v191, v239
	v_cvt_pk_bf16_f32 v122, v238, v239
	v_add_f32_e32 v190, v190, v240
	s_waitcnt lgkmcnt(7)
	v_mfma_f32_32x32x16_bf16 v[82:97], v[208:211], v[146:149], v[82:97]
	ds_read_b128 v[182:185], v232 offset:45056
	v_add_f32_e32 v191, v191, v241
	v_cvt_pk_bf16_f32 v123, v240, v241
	v_add_f32_e32 v190, v190, v242
	v_add_f32_e32 v191, v191, v243
	s_waitcnt lgkmcnt(7)
	v_mfma_f32_32x32x16_bf16 v[98:113], v[212:215], v[158:161], v[0:15]
	ds_read_b128 v[186:189], v233 offset:32768
	v_cvt_pk_bf16_f32 v124, v242, v243
	v_add_f32_e32 v190, v190, v244
	v_add_f32_e32 v191, v191, v245
	v_cvt_pk_bf16_f32 v125, v244, v245
	s_waitcnt lgkmcnt(7)
	v_mfma_f32_32x32x16_bf16 v[98:113], v[216:219], v[154:157], v[98:113]
	ds_read_b128 v[200:203], v233 offset:36864
	v_add_f32_e32 v190, v190, v130
	v_add_f32_e32 v191, v191, v131
	v_cvt_pk_bf16_f32 v126, v130, v131
	v_add_f32_e32 v190, v190, v132
	s_waitcnt lgkmcnt(7)
	v_mfma_f32_32x32x16_bf16 v[98:113], v[220:223], v[150:153], v[98:113]
	ds_read_b128 v[204:207], v233 offset:40960
	v_add_f32_e32 v191, v191, v133
	v_cvt_pk_bf16_f32 v127, v132, v133
	v_add_f32_e32 v190, v190, v134
	v_add_f32_e32 v191, v191, v135
	s_waitcnt lgkmcnt(7)
	v_mfma_f32_32x32x16_bf16 v[98:113], v[224:227], v[146:149], v[98:113]
	ds_read_b128 v[208:211], v233 offset:45056
	v_cvt_pk_bf16_f32 v128, v134, v135
	v_add_f32_e32 v190, v190, v136
	v_add_f32_e32 v191, v191, v137
	v_cvt_pk_bf16_f32 v129, v136, v137
	s_waitcnt vmcnt(2)
	s_barrier
; template <int MODE> __device__ __forceinline__ void diff_attn_item(const bf16* __restrict__ Qb, const bf16* __restrict__ Kh, const bf16* __restrict__ Vh, ...
;     ...
;   for (int j = 0; j < NTL; ++j) {
;     const bool has1 = (j + 1 < NTL), has2 = (j + 2 < NTL);
;     if (has2 && MODE == 0) SLOADW(s_wr, (j + 2) * KVBLK);
;     bf16x8 f0, f1, f2, f3;
;     if (has1) qkt(pn0, pn1, lds + s_nxt * SHM_BUF + SHM_KV, qr, r32, hi, map, negM);
;     sm_half<MODE>(pc0, lsum, f0, f1);
;     const char* vt = lds + s_cur * SHM_BUF;
;     pv_b128(o, vt + voff[0], f0); pv_b128(o, vt + voff[1], f1);
;     sm_half<MODE>(pc1, lsum, f2, f3);
;     pv_b128(o, vt + voff[2], f2); pv_b128(o, vt + voff[3], f3);
;     asm volatile("s_waitcnt vmcnt(0)" ::: "memory");
;     __syncthreads();
;     pc0 = pn0; pc1 = pn1;
;     const int t = s_cur; s_cur = s_nxt; s_nxt = s_wr; s_wr = t;
	s_waitcnt lgkmcnt(7)
	v_mfma_f32_32x32x16_bf16 v[66:81], v[166:169], v[114:117], v[66:81]
	s_add_u32 m0, s14, 0x4000
	ds_read_b128 v[212:215], v234 offset:32768
	global_load_lds_dwordx4 v246, s[10:11]
	v_exp_f32_e32 v130, v82
	v_exp_f32_e32 v131, v83
	v_add_f32_e32 v190, v190, v130
	s_waitcnt lgkmcnt(7)
	v_mfma_f32_32x32x16_bf16 v[50:65], v[170:173], v[114:117], v[50:65]
	s_add_u32 m0, s14, 0x6000
	ds_read_b128 v[216:219], v234 offset:36864
	global_load_lds_dwordx4 v247, s[10:11]
	s_add_u32 s10, s10, 0x4000
	s_addc_u32 s11, s11, 0
	v_exp_f32_e32 v132, v84
	v_exp_f32_e32 v133, v85
	v_add_f32_e32 v191, v191, v131
	s_waitcnt lgkmcnt(7)
	v_mfma_f32_32x32x16_bf16 v[34:49], v[178:181], v[114:117], v[34:49]
	s_add_u32 m0, s14, 0xc000
	ds_read_b128 v[220:223], v234 offset:40960
	global_load_lds_dwordx4 v236, s[8:9]
	v_exp_f32_e32 v134, v86
	v_exp_f32_e32 v135, v87
	v_add_f32_e32 v190, v190, v132
	s_waitcnt lgkmcnt(7)
	v_mfma_f32_32x32x16_bf16 v[18:33], v[182:185], v[114:117], v[18:33]
	s_add_u32 m0, s14, 0xe000
	ds_read_b128 v[224:227], v234 offset:45056
	global_load_lds_dwordx4 v237, s[8:9]
	s_add_u32 s8, s8, 0x4000
	s_addc_u32 s9, s9, 0
	v_exp_f32_e32 v136, v88
	v_exp_f32_e32 v137, v89
	v_add_f32_e32 v191, v191, v133
	s_waitcnt lgkmcnt(7)
	v_mfma_f32_32x32x16_bf16 v[66:81], v[186:189], v[118:121], v[66:81]
	ds_read_b128 v[166:169], v235 offset:32768
	v_exp_f32_e32 v138, v90
	v_exp_f32_e32 v139, v91
	v_cvt_pk_bf16_f32 v114, v130, v131
	s_waitcnt lgkmcnt(7)
	v_mfma_f32_32x32x16_bf16 v[50:65], v[200:203], v[118:121], v[50:65]
	ds_read_b128 v[170:173], v235 offset:36864
	v_exp_f32_e32 v140, v92
	v_exp_f32_e32 v141, v93
	v_cvt_pk_bf16_f32 v115, v132, v133
	s_waitcnt lgkmcnt(7)
	v_mfma_f32_32x32x16_bf16 v[34:49], v[204:207], v[118:121], v[34:49]
	ds_read_b128 v[178:181], v235 offset:40960
	v_exp_f32_e32 v142, v94
	v_exp_f32_e32 v143, v95
	v_add_f32_e32 v190, v190, v134
	s_waitcnt lgkmcnt(7)
	v_mfma_f32_32x32x16_bf16 v[18:33], v[208:211], v[118:121], v[18:33]
	ds_read_b128 v[182:185], v235 offset:45056
	v_exp_f32_e32 v144, v96
	v_exp_f32_e32 v145, v97
	v_add_f32_e32 v191, v191, v135
	s_waitcnt lgkmcnt(7)
	v_mfma_f32_32x32x16_bf16 v[66:81], v[212:215], v[122:125], v[66:81]
	ds_read_b128 v[186:189], v228 offset:16384
	v_exp_f32_e32 v238, v98
	v_exp_f32_e32 v239, v99
	v_cvt_pk_bf16_f32 v116, v134, v135
	s_waitcnt lgkmcnt(7)
	v_mfma_f32_32x32x16_bf16 v[50:65], v[216:219], v[122:125], v[50:65]
	ds_read_b128 v[200:203], v229 offset:16384
	v_exp_f32_e32 v240, v100
	v_exp_f32_e32 v241, v101
	v_add_f32_e32 v190, v190, v136
	s_waitcnt lgkmcnt(7)
	v_mfma_f32_32x32x16_bf16 v[34:49], v[220:223], v[122:125], v[34:49]
	ds_read_b128 v[204:207], v230 offset:16384
	v_exp_f32_e32 v242, v102
	v_exp_f32_e32 v243, v103
	v_add_f32_e32 v191, v191, v137
	s_waitcnt lgkmcnt(7)
	v_mfma_f32_32x32x16_bf16 v[18:33], v[224:227], v[122:125], v[18:33]
	ds_read_b128 v[208:211], v231 offset:16384
	v_exp_f32_e32 v244, v104
	v_exp_f32_e32 v245, v105
	v_cvt_pk_bf16_f32 v117, v136, v137
	s_waitcnt lgkmcnt(7)
	v_mfma_f32_32x32x16_bf16 v[66:81], v[166:169], v[126:129], v[66:81]
	ds_read_b128 v[212:215], v228 offset:24576
	v_exp_f32_e32 v130, v106
	v_exp_f32_e32 v131, v107
	v_add_f32_e32 v190, v190, v138
	s_waitcnt lgkmcnt(7)
	v_mfma_f32_32x32x16_bf16 v[50:65], v[170:173], v[126:129], v[50:65]
	ds_read_b128 v[216:219], v229 offset:24576
	v_exp_f32_e32 v132, v108
	v_exp_f32_e32 v133, v109
	v_add_f32_e32 v191, v191, v139
	s_waitcnt lgkmcnt(7)
	v_mfma_f32_32x32x16_bf16 v[34:49], v[178:181], v[126:129], v[34:49]
	ds_read_b128 v[220:223], v230 offset:24576
	v_exp_f32_e32 v134, v110
	v_exp_f32_e32 v135, v111
	v_add_f32_e32 v190, v190, v140
	s_waitcnt lgkmcnt(7)
	v_mfma_f32_32x32x16_bf16 v[18:33], v[182:185], v[126:129], v[18:33]
	ds_read_b128 v[224:227], v231 offset:24576
	v_exp_f32_e32 v136, v112
	v_exp_f32_e32 v137, v113
	v_add_f32_e32 v191, v191, v141
	s_waitcnt lgkmcnt(7)
	v_mfma_f32_32x32x16_bf16 v[82:97], v[186:189], v[158:161], v[0:15]
	ds_read_b128 v[166:169], v232 offset:0
	v_cvt_pk_bf16_f32 v118, v138, v139
	v_cvt_pk_bf16_f32 v119, v140, v141
	v_add_f32_e32 v190, v190, v142
	v_add_f32_e32 v191, v191, v143
	s_waitcnt lgkmcnt(7)
	v_mfma_f32_32x32x16_bf16 v[82:97], v[200:203], v[154:157], v[82:97]
	ds_read_b128 v[170:173], v232 offset:4096
	v_cvt_pk_bf16_f32 v120, v142, v143
	v_add_f32_e32 v190, v190, v144
	v_add_f32_e32 v191, v191, v145
	v_cvt_pk_bf16_f32 v121, v144, v145
	s_waitcnt lgkmcnt(7)
	v_mfma_f32_32x32x16_bf16 v[82:97], v[204:207], v[150:153], v[82:97]
	ds_read_b128 v[178:181], v232 offset:8192
	v_add_f32_e32 v190, v190, v238
	v_add_f32_e32 v191, v191, v239
	v_cvt_pk_bf16_f32 v122, v238, v239
	v_add_f32_e32 v190, v190, v240
	s_waitcnt lgkmcnt(7)
	v_mfma_f32_32x32x16_bf16 v[82:97], v[208:211], v[146:149], v[82:97]
	ds_read_b128 v[182:185], v232 offset:12288
	v_add_f32_e32 v191, v191, v241
	v_cvt_pk_bf16_f32 v123, v240, v241
	v_add_f32_e32 v190, v190, v242
	v_add_f32_e32 v191, v191, v243
	s_waitcnt lgkmcnt(7)
	v_mfma_f32_32x32x16_bf16 v[98:113], v[212:215], v[158:161], v[0:15]
	ds_read_b128 v[186:189], v233 offset:0
	v_cvt_pk_bf16_f32 v124, v242, v243
	v_add_f32_e32 v190, v190, v244
	v_add_f32_e32 v191, v191, v245
	v_cvt_pk_bf16_f32 v125, v244, v245
	s_waitcnt lgkmcnt(7)
	v_mfma_f32_32x32x16_bf16 v[98:113], v[216:219], v[154:157], v[98:113]
	ds_read_b128 v[200:203], v233 offset:4096
	v_add_f32_e32 v190, v190, v130
	v_add_f32_e32 v191, v191, v131
	v_cvt_pk_bf16_f32 v126, v130, v131
	v_add_f32_e32 v190, v190, v132
	s_waitcnt lgkmcnt(7)
	v_mfma_f32_32x32x16_bf16 v[98:113], v[220:223], v[150:153], v[98:113]
	ds_read_b128 v[204:207], v233 offset:8192
	v_add_f32_e32 v191, v191, v133
	v_cvt_pk_bf16_f32 v127, v132, v133
	v_add_f32_e32 v190, v190, v134
	v_add_f32_e32 v191, v191, v135
	s_waitcnt lgkmcnt(7)
	v_mfma_f32_32x32x16_bf16 v[98:113], v[224:227], v[146:149], v[98:113]
	ds_read_b128 v[208:211], v233 offset:12288
	v_cvt_pk_bf16_f32 v128, v134, v135
	v_add_f32_e32 v190, v190, v136
	v_add_f32_e32 v191, v191, v137
	v_cvt_pk_bf16_f32 v129, v136, v137
	s_waitcnt vmcnt(2)
	s_sub_u32 s15, s15, 1
	s_cmp_lg_u32 s15, 0
	s_cbranch_scc1 .Lda0_loop
; template <int MODE> __device__ __forceinline__ void diff_attn_item(const bf16* __restrict__ Qb, const bf16* __restrict__ Kh, const bf16* __restrict__ Vh, ...
;     ...
;   for (int j = 0; j < NTL; ++j) {
;     const bool has1 = (j + 1 < NTL), has2 = (j + 2 < NTL);
;     if (has2 && MODE == 0) SLOADW(s_wr, (j + 2) * KVBLK);
;     bf16x8 f0, f1, f2, f3;
;     if (has1) qkt(pn0, pn1, lds + s_nxt * SHM_BUF + SHM_KV, qr, r32, hi, map, negM);
;     sm_half<MODE>(pc0, lsum, f0, f1);
;     const char* vt = lds + s_cur * SHM_BUF;
;     pv_b128(o, vt + voff[0], f0); pv_b128(o, vt + voff[1], f1);
;     sm_half<MODE>(pc1, lsum, f2, f3);
;     pv_b128(o, vt + voff[2], f2); pv_b128(o, vt + voff[3], f3);
;     asm volatile("s_waitcnt vmcnt(0)" ::: "memory");
;     __syncthreads();
;     pc0 = pn0; pc1 = pn1;
;     const int t = s_cur; s_cur = s_nxt; s_nxt = s_wr; s_wr = t;
	s_barrier
	s_waitcnt lgkmcnt(7)
	v_mfma_f32_32x32x16_bf16 v[66:81], v[166:169], v[114:117], v[66:81]
	s_add_u32 m0, s14, 0x8000
	ds_read_b128 v[212:215], v234 offset:0
	global_load_lds_dwordx4 v246, s[10:11]
	v_exp_f32_e32 v130, v82
	v_exp_f32_e32 v131, v83
	v_add_f32_e32 v190, v190, v130
	s_waitcnt lgkmcnt(7)
	v_mfma_f32_32x32x16_bf16 v[50:65], v[170:173], v[114:117], v[50:65]
	s_add_u32 m0, s14, 0xa000
	ds_read_b128 v[216:219], v234 offset:4096
	global_load_lds_dwordx4 v247, s[10:11]
	s_add_u32 s10, s10, 0x4000
	s_addc_u32 s11, s11, 0
	v_exp_f32_e32 v132, v84
	v_exp_f32_e32 v133, v85
	v_add_f32_e32 v191, v191, v131
	s_waitcnt lgkmcnt(7)
	v_mfma_f32_32x32x16_bf16 v[34:49], v[178:181], v[114:117], v[34:49]
	s_add_u32 m0, s14, 0x10000
	ds_read_b128 v[220:223], v234 offset:8192
	global_load_lds_dwordx4 v236, s[8:9]
	v_exp_f32_e32 v134, v86
	v_exp_f32_e32 v135, v87
	v_add_f32_e32 v190, v190, v132
	s_waitcnt lgkmcnt(7)
	v_mfma_f32_32x32x16_bf16 v[18:33], v[182:185], v[114:117], v[18:33]
	s_add_u32 m0, s14, 0x12000
	ds_read_b128 v[224:227], v234 offset:12288
	global_load_lds_dwordx4 v237, s[8:9]
	s_add_u32 s8, s8, 0x4000
	s_addc_u32 s9, s9, 0
	v_exp_f32_e32 v136, v88
	v_exp_f32_e32 v137, v89
	v_add_f32_e32 v191, v191, v133
	s_waitcnt lgkmcnt(7)
	v_mfma_f32_32x32x16_bf16 v[66:81], v[186:189], v[118:121], v[66:81]
	ds_read_b128 v[166:169], v235 offset:0
	v_exp_f32_e32 v138, v90
	v_exp_f32_e32 v139, v91
	v_cvt_pk_bf16_f32 v114, v130, v131
	s_waitcnt lgkmcnt(7)
	v_mfma_f32_32x32x16_bf16 v[50:65], v[200:203], v[118:121], v[50:65]
	ds_read_b128 v[170:173], v235 offset:4096
	v_exp_f32_e32 v140, v92
	v_exp_f32_e32 v141, v93
	v_cvt_pk_bf16_f32 v115, v132, v133
	s_waitcnt lgkmcnt(7)
	v_mfma_f32_32x32x16_bf16 v[34:49], v[204:207], v[118:121], v[34:49]
	ds_read_b128 v[178:181], v235 offset:8192
	v_exp_f32_e32 v142, v94
	v_exp_f32_e32 v143, v95
	v_add_f32_e32 v190, v190, v134
	s_waitcnt lgkmcnt(7)
	v_mfma_f32_32x32x16_bf16 v[18:33], v[208:211], v[118:121], v[18:33]
	ds_read_b128 v[182:185], v235 offset:12288
	v_exp_f32_e32 v144, v96
	v_exp_f32_e32 v145, v97
	v_add_f32_e32 v191, v191, v135
	s_waitcnt lgkmcnt(7)
	v_mfma_f32_32x32x16_bf16 v[66:81], v[212:215], v[122:125], v[66:81]
	ds_read_b128 v[186:189], v228 offset:32768
	v_exp_f32_e32 v238, v98
	v_exp_f32_e32 v239, v99
	v_cvt_pk_bf16_f32 v116, v134, v135
	s_waitcnt lgkmcnt(7)
	v_mfma_f32_32x32x16_bf16 v[50:65], v[216:219], v[122:125], v[50:65]
	ds_read_b128 v[200:203], v229 offset:32768
	v_exp_f32_e32 v240, v100
	v_exp_f32_e32 v241, v101
	v_add_f32_e32 v190, v190, v136
	s_waitcnt lgkmcnt(7)
	v_mfma_f32_32x32x16_bf16 v[34:49], v[220:223], v[122:125], v[34:49]
	ds_read_b128 v[204:207], v230 offset:32768
	v_exp_f32_e32 v242, v102
	v_exp_f32_e32 v243, v103
	v_add_f32_e32 v191, v191, v137
	s_waitcnt lgkmcnt(7)
	v_mfma_f32_32x32x16_bf16 v[18:33], v[224:227], v[122:125], v[18:33]
	ds_read_b128 v[208:211], v231 offset:32768
	v_exp_f32_e32 v244, v104
	v_exp_f32_e32 v245, v105
	v_cvt_pk_bf16_f32 v117, v136, v137
	s_waitcnt lgkmcnt(7)
	v_mfma_f32_32x32x16_bf16 v[66:81], v[166:169], v[126:129], v[66:81]
	ds_read_b128 v[212:215], v228 offset:40960
	v_exp_f32_e32 v130, v106
	v_exp_f32_e32 v131, v107
	v_add_f32_e32 v190, v190, v138
	s_waitcnt lgkmcnt(7)
	v_mfma_f32_32x32x16_bf16 v[50:65], v[170:173], v[126:129], v[50:65]
	ds_read_b128 v[216:219], v229 offset:40960
	v_exp_f32_e32 v132, v108
	v_exp_f32_e32 v133, v109
	v_add_f32_e32 v191, v191, v139
	s_waitcnt lgkmcnt(7)
	v_mfma_f32_32x32x16_bf16 v[34:49], v[178:181], v[126:129], v[34:49]
	ds_read_b128 v[220:223], v230 offset:40960
	v_exp_f32_e32 v134, v110
	v_exp_f32_e32 v135, v111
	v_add_f32_e32 v190, v190, v140
	s_waitcnt lgkmcnt(7)
	v_mfma_f32_32x32x16_bf16 v[18:33], v[182:185], v[126:129], v[18:33]
	ds_read_b128 v[224:227], v231 offset:40960
	v_exp_f32_e32 v136, v112
	v_exp_f32_e32 v137, v113
	v_add_f32_e32 v191, v191, v141
	s_waitcnt lgkmcnt(7)
	v_mfma_f32_32x32x16_bf16 v[82:97], v[186:189], v[158:161], v[0:15]
	ds_read_b128 v[166:169], v232 offset:16384
	v_cvt_pk_bf16_f32 v118, v138, v139
	v_cvt_pk_bf16_f32 v119, v140, v141
	v_add_f32_e32 v190, v190, v142
	v_add_f32_e32 v191, v191, v143
	s_waitcnt lgkmcnt(7)
	v_mfma_f32_32x32x16_bf16 v[82:97], v[200:203], v[154:157], v[82:97]
	ds_read_b128 v[170:173], v232 offset:20480
	v_cvt_pk_bf16_f32 v120, v142, v143
	v_add_f32_e32 v190, v190, v144
	v_add_f32_e32 v191, v191, v145
	v_cvt_pk_bf16_f32 v121, v144, v145
	s_waitcnt lgkmcnt(7)
	v_mfma_f32_32x32x16_bf16 v[82:97], v[204:207], v[150:153], v[82:97]
	ds_read_b128 v[178:181], v232 offset:24576
	v_add_f32_e32 v190, v190, v238
	v_add_f32_e32 v191, v191, v239
	v_cvt_pk_bf16_f32 v122, v238, v239
	v_add_f32_e32 v190, v190, v240
	s_waitcnt lgkmcnt(7)
	v_mfma_f32_32x32x16_bf16 v[82:97], v[208:211], v[146:149], v[82:97]
	ds_read_b128 v[182:185], v232 offset:28672
	v_add_f32_e32 v191, v191, v241
	v_cvt_pk_bf16_f32 v123, v240, v241
	v_add_f32_e32 v190, v190, v242
	v_add_f32_e32 v191, v191, v243
	s_waitcnt lgkmcnt(7)
	v_mfma_f32_32x32x16_bf16 v[98:113], v[212:215], v[158:161], v[0:15]
	ds_read_b128 v[186:189], v233 offset:16384
	v_cvt_pk_bf16_f32 v124, v242, v243
	v_add_f32_e32 v190, v190, v244
	v_add_f32_e32 v191, v191, v245
	v_cvt_pk_bf16_f32 v125, v244, v245
	s_waitcnt lgkmcnt(7)
	v_mfma_f32_32x32x16_bf16 v[98:113], v[216:219], v[154:157], v[98:113]
	ds_read_b128 v[200:203], v233 offset:20480
	v_add_f32_e32 v190, v190, v130
	v_add_f32_e32 v191, v191, v131
	v_cvt_pk_bf16_f32 v126, v130, v131
	v_add_f32_e32 v190, v190, v132
	s_waitcnt lgkmcnt(7)
	v_mfma_f32_32x32x16_bf16 v[98:113], v[220:223], v[150:153], v[98:113]
	ds_read_b128 v[204:207], v233 offset:24576
	v_add_f32_e32 v191, v191, v133
	v_cvt_pk_bf16_f32 v127, v132, v133
	v_add_f32_e32 v190, v190, v134
	v_add_f32_e32 v191, v191, v135
	s_waitcnt lgkmcnt(7)
	v_mfma_f32_32x32x16_bf16 v[98:113], v[224:227], v[146:149], v[98:113]
	ds_read_b128 v[208:211], v233 offset:28672
	v_cvt_pk_bf16_f32 v128, v134, v135
	v_add_f32_e32 v190, v190, v136
	v_add_f32_e32 v191, v191, v137
	v_cvt_pk_bf16_f32 v129, v136, v137
	s_waitcnt vmcnt(2)
	s_barrier
; template <int MODE> __device__ __forceinline__ void diff_attn_item(const bf16* __restrict__ Qb, const bf16* __restrict__ Kh, const bf16* __restrict__ Vh, ...
;     ...
;   for (int j = 0; j < NTL; ++j) {
;     const bool has1 = (j + 1 < NTL), has2 = (j + 2 < NTL);
;     if (has2 && MODE == 0) SLOADW(s_wr, (j + 2) * KVBLK);
;     bf16x8 f0, f1, f2, f3;
;     if (has1) qkt(pn0, pn1, lds + s_nxt * SHM_BUF + SHM_KV, qr, r32, hi, map, negM);
;     sm_half<MODE>(pc0, lsum, f0, f1);
;     const char* vt = lds + s_cur * SHM_BUF;
;     pv_b128(o, vt + voff[0], f0); pv_b128(o, vt + voff[1], f1);
;     sm_half<MODE>(pc1, lsum, f2, f3);
;     pv_b128(o, vt + voff[2], f2); pv_b128(o, vt + voff[3], f3);
;     asm volatile("s_waitcnt vmcnt(0)" ::: "memory");
;     __syncthreads();
;     pc0 = pn0; pc1 = pn1;
;     const int t = s_cur; s_cur = s_nxt; s_nxt = s_wr; s_wr = t;
	s_waitcnt lgkmcnt(7)
	v_mfma_f32_32x32x16_bf16 v[66:81], v[166:169], v[114:117], v[66:81]
	s_mov_b32 m0, s14
	ds_read_b128 v[212:215], v234 offset:16384
	global_load_lds_dwordx4 v246, s[10:11]
	v_exp_f32_e32 v130, v82
	v_exp_f32_e32 v131, v83
	v_add_f32_e32 v190, v190, v130
	s_waitcnt lgkmcnt(7)
	v_mfma_f32_32x32x16_bf16 v[50:65], v[170:173], v[114:117], v[50:65]
	s_add_u32 m0, s14, 0x2000
	ds_read_b128 v[216:219], v234 offset:20480
	global_load_lds_dwordx4 v247, s[10:11]
	s_add_u32 s10, s10, 0x4000
	s_addc_u32 s11, s11, 0
	v_exp_f32_e32 v132, v84
	v_exp_f32_e32 v133, v85
	v_add_f32_e32 v191, v191, v131
	s_waitcnt lgkmcnt(7)
	v_mfma_f32_32x32x16_bf16 v[34:49], v[178:181], v[114:117], v[34:49]
	s_add_u32 m0, s14, 0x14000
	ds_read_b128 v[220:223], v234 offset:24576
	global_load_lds_dwordx4 v236, s[8:9]
	v_exp_f32_e32 v134, v86
	v_exp_f32_e32 v135, v87
	v_add_f32_e32 v190, v190, v132
	s_waitcnt lgkmcnt(7)
	v_mfma_f32_32x32x16_bf16 v[18:33], v[182:185], v[114:117], v[18:33]
	s_add_u32 m0, s14, 0x16000
	ds_read_b128 v[224:227], v234 offset:28672
	global_load_lds_dwordx4 v237, s[8:9]
	s_add_u32 s8, s8, 0x4000
	s_addc_u32 s9, s9, 0
	v_exp_f32_e32 v136, v88
	v_exp_f32_e32 v137, v89
	v_add_f32_e32 v191, v191, v133
	s_waitcnt lgkmcnt(7)
	v_mfma_f32_32x32x16_bf16 v[66:81], v[186:189], v[118:121], v[66:81]
	ds_read_b128 v[166:169], v235 offset:16384
	v_exp_f32_e32 v138, v90
	v_exp_f32_e32 v139, v91
	v_cvt_pk_bf16_f32 v114, v130, v131
	s_waitcnt lgkmcnt(7)
	v_mfma_f32_32x32x16_bf16 v[50:65], v[200:203], v[118:121], v[50:65]
	ds_read_b128 v[170:173], v235 offset:20480
	v_exp_f32_e32 v140, v92
	v_exp_f32_e32 v141, v93
	v_cvt_pk_bf16_f32 v115, v132, v133
	s_waitcnt lgkmcnt(7)
	v_mfma_f32_32x32x16_bf16 v[34:49], v[204:207], v[118:121], v[34:49]
	ds_read_b128 v[178:181], v235 offset:24576
	v_exp_f32_e32 v142, v94
	v_exp_f32_e32 v143, v95
	v_add_f32_e32 v190, v190, v134
	s_waitcnt lgkmcnt(7)
	v_mfma_f32_32x32x16_bf16 v[18:33], v[208:211], v[118:121], v[18:33]
	ds_read_b128 v[182:185], v235 offset:28672
	v_exp_f32_e32 v144, v96
	v_exp_f32_e32 v145, v97
	v_add_f32_e32 v191, v191, v135
	s_waitcnt lgkmcnt(7)
	v_mfma_f32_32x32x16_bf16 v[66:81], v[212:215], v[122:125], v[66:81]
	ds_read_b128 v[186:189], v228 offset:0
	v_exp_f32_e32 v238, v98
	v_exp_f32_e32 v239, v99
	v_cvt_pk_bf16_f32 v116, v134, v135
	s_waitcnt lgkmcnt(7)
	v_mfma_f32_32x32x16_bf16 v[50:65], v[216:219], v[122:125], v[50:65]
	ds_read_b128 v[200:203], v229 offset:0
	v_exp_f32_e32 v240, v100
	v_exp_f32_e32 v241, v101
	v_add_f32_e32 v190, v190, v136
	s_waitcnt lgkmcnt(7)
	v_mfma_f32_32x32x16_bf16 v[34:49], v[220:223], v[122:125], v[34:49]
	ds_read_b128 v[204:207], v230 offset:0
	v_exp_f32_e32 v242, v102
	v_exp_f32_e32 v243, v103
	v_add_f32_e32 v191, v191, v137
	s_waitcnt lgkmcnt(7)
	v_mfma_f32_32x32x16_bf16 v[18:33], v[224:227], v[122:125], v[18:33]
	ds_read_b128 v[208:211], v231 offset:0
	v_exp_f32_e32 v244, v104
	v_exp_f32_e32 v245, v105
	v_cvt_pk_bf16_f32 v117, v136, v137
	s_waitcnt lgkmcnt(7)
	v_mfma_f32_32x32x16_bf16 v[66:81], v[166:169], v[126:129], v[66:81]
	ds_read_b128 v[212:215], v228 offset:8192
	v_exp_f32_e32 v130, v106
	v_exp_f32_e32 v131, v107
	v_add_f32_e32 v190, v190, v138
	s_waitcnt lgkmcnt(7)
	v_mfma_f32_32x32x16_bf16 v[50:65], v[170:173], v[126:129], v[50:65]
	ds_read_b128 v[216:219], v229 offset:8192
	v_exp_f32_e32 v132, v108
	v_exp_f32_e32 v133, v109
	v_add_f32_e32 v191, v191, v139
	s_waitcnt lgkmcnt(7)
	v_mfma_f32_32x32x16_bf16 v[34:49], v[178:181], v[126:129], v[34:49]
	ds_read_b128 v[220:223], v230 offset:8192
	v_exp_f32_e32 v134, v110
	v_exp_f32_e32 v135, v111
	v_add_f32_e32 v190, v190, v140
	s_waitcnt lgkmcnt(7)
	v_mfma_f32_32x32x16_bf16 v[18:33], v[182:185], v[126:129], v[18:33]
	ds_read_b128 v[224:227], v231 offset:8192
	v_exp_f32_e32 v136, v112
	v_exp_f32_e32 v137, v113
	v_add_f32_e32 v191, v191, v141
	s_waitcnt lgkmcnt(7)
	v_mfma_f32_32x32x16_bf16 v[82:97], v[186:189], v[158:161], v[0:15]
	ds_read_b128 v[166:169], v232 offset:32768
	v_cvt_pk_bf16_f32 v118, v138, v139
	v_cvt_pk_bf16_f32 v119, v140, v141
	v_add_f32_e32 v190, v190, v142
	v_add_f32_e32 v191, v191, v143
	s_waitcnt lgkmcnt(7)
	v_mfma_f32_32x32x16_bf16 v[82:97], v[200:203], v[154:157], v[82:97]
	ds_read_b128 v[170:173], v232 offset:36864
	v_cvt_pk_bf16_f32 v120, v142, v143
	v_add_f32_e32 v190, v190, v144
	v_add_f32_e32 v191, v191, v145
	v_cvt_pk_bf16_f32 v121, v144, v145
	s_waitcnt lgkmcnt(7)
	v_mfma_f32_32x32x16_bf16 v[82:97], v[204:207], v[150:153], v[82:97]
	ds_read_b128 v[178:181], v232 offset:40960
	v_add_f32_e32 v190, v190, v238
	v_add_f32_e32 v191, v191, v239
	v_cvt_pk_bf16_f32 v122, v238, v239
	v_add_f32_e32 v190, v190, v240
	s_waitcnt lgkmcnt(7)
	v_mfma_f32_32x32x16_bf16 v[82:97], v[208:211], v[146:149], v[82:97]
	ds_read_b128 v[182:185], v232 offset:45056
	v_add_f32_e32 v191, v191, v241
	v_cvt_pk_bf16_f32 v123, v240, v241
	v_add_f32_e32 v190, v190, v242
	v_add_f32_e32 v191, v191, v243
	s_waitcnt lgkmcnt(7)
	v_mfma_f32_32x32x16_bf16 v[98:113], v[212:215], v[158:161], v[0:15]
	ds_read_b128 v[186:189], v233 offset:32768
	v_cvt_pk_bf16_f32 v124, v242, v243
	v_add_f32_e32 v190, v190, v244
	v_add_f32_e32 v191, v191, v245
	v_cvt_pk_bf16_f32 v125, v244, v245
	s_waitcnt lgkmcnt(7)
	v_mfma_f32_32x32x16_bf16 v[98:113], v[216:219], v[154:157], v[98:113]
	ds_read_b128 v[200:203], v233 offset:36864
	v_add_f32_e32 v190, v190, v130
	v_add_f32_e32 v191, v191, v131
	v_cvt_pk_bf16_f32 v126, v130, v131
	v_add_f32_e32 v190, v190, v132
	s_waitcnt lgkmcnt(7)
	v_mfma_f32_32x32x16_bf16 v[98:113], v[220:223], v[150:153], v[98:113]
	ds_read_b128 v[204:207], v233 offset:40960
	v_add_f32_e32 v191, v191, v133
	v_cvt_pk_bf16_f32 v127, v132, v133
	v_add_f32_e32 v190, v190, v134
	v_add_f32_e32 v191, v191, v135
	s_waitcnt lgkmcnt(7)
	v_mfma_f32_32x32x16_bf16 v[98:113], v[224:227], v[146:149], v[98:113]
	ds_read_b128 v[208:211], v233 offset:45056
	v_cvt_pk_bf16_f32 v128, v134, v135
	v_add_f32_e32 v190, v190, v136
	v_add_f32_e32 v191, v191, v137
	v_cvt_pk_bf16_f32 v129, v136, v137
	s_waitcnt vmcnt(2)
	s_barrier
; template <int MODE> __device__ __forceinline__ void diff_attn_item(const bf16* __restrict__ Qb, const bf16* __restrict__ Kh, const bf16* __restrict__ Vh, ...
;     ...
;   for (int j = 0; j < NTL; ++j) {
;     const bool has1 = (j + 1 < NTL), has2 = (j + 2 < NTL);
;     if (has2 && MODE == 0) SLOADW(s_wr, (j + 2) * KVBLK);
;     bf16x8 f0, f1, f2, f3;
;     if (has1) qkt(pn0, pn1, lds + s_nxt * SHM_BUF + SHM_KV, qr, r32, hi, map, negM);
;     sm_half<MODE>(pc0, lsum, f0, f1);
;     const char* vt = lds + s_cur * SHM_BUF;
;     pv_b128(o, vt + voff[0], f0); pv_b128(o, vt + voff[1], f1);
;     sm_half<MODE>(pc1, lsum, f2, f3);
;     pv_b128(o, vt + voff[2], f2); pv_b128(o, vt + voff[3], f3);
;     asm volatile("s_waitcnt vmcnt(0)" ::: "memory");
;     __syncthreads();
;     pc0 = pn0; pc1 = pn1;
;     const int t = s_cur; s_cur = s_nxt; s_nxt = s_wr; s_wr = t;
	s_waitcnt lgkmcnt(7)
	v_mfma_f32_32x32x16_bf16 v[66:81], v[166:169], v[114:117], v[66:81]
	s_add_u32 m0, s14, 0x4000
	ds_read_b128 v[212:215], v234 offset:32768
	global_load_lds_dwordx4 v246, s[10:11]
	v_exp_f32_e32 v130, v82
	v_exp_f32_e32 v131, v83
	v_add_f32_e32 v190, v190, v130
	s_waitcnt lgkmcnt(7)
	v_mfma_f32_32x32x16_bf16 v[50:65], v[170:173], v[114:117], v[50:65]
	s_add_u32 m0, s14, 0x6000
	ds_read_b128 v[216:219], v234 offset:36864
	global_load_lds_dwordx4 v247, s[10:11]
	s_add_u32 s10, s10, 0x4000
	s_addc_u32 s11, s11, 0
	v_exp_f32_e32 v132, v84
	v_exp_f32_e32 v133, v85
	v_add_f32_e32 v191, v191, v131
	s_waitcnt lgkmcnt(7)
	v_mfma_f32_32x32x16_bf16 v[34:49], v[178:181], v[114:117], v[34:49]
	ds_read_b128 v[220:223], v234 offset:40960
	v_exp_f32_e32 v134, v86
	v_exp_f32_e32 v135, v87
	v_add_f32_e32 v190, v190, v132
	s_waitcnt lgkmcnt(7)
	v_mfma_f32_32x32x16_bf16 v[18:33], v[182:185], v[114:117], v[18:33]
	ds_read_b128 v[224:227], v234 offset:45056
	v_exp_f32_e32 v136, v88
	v_exp_f32_e32 v137, v89
	v_add_f32_e32 v191, v191, v133
	s_waitcnt lgkmcnt(7)
	v_mfma_f32_32x32x16_bf16 v[66:81], v[186:189], v[118:121], v[66:81]
	ds_read_b128 v[166:169], v235 offset:32768
	v_exp_f32_e32 v138, v90
	v_exp_f32_e32 v139, v91
	v_cvt_pk_bf16_f32 v114, v130, v131
	s_waitcnt lgkmcnt(7)
	v_mfma_f32_32x32x16_bf16 v[50:65], v[200:203], v[118:121], v[50:65]
	ds_read_b128 v[170:173], v235 offset:36864
	v_exp_f32_e32 v140, v92
	v_exp_f32_e32 v141, v93
	v_cvt_pk_bf16_f32 v115, v132, v133
	s_waitcnt lgkmcnt(7)
	v_mfma_f32_32x32x16_bf16 v[34:49], v[204:207], v[118:121], v[34:49]
	ds_read_b128 v[178:181], v235 offset:40960
	v_exp_f32_e32 v142, v94
	v_exp_f32_e32 v143, v95
	v_add_f32_e32 v190, v190, v134
	s_waitcnt lgkmcnt(7)
	v_mfma_f32_32x32x16_bf16 v[18:33], v[208:211], v[118:121], v[18:33]
	ds_read_b128 v[182:185], v235 offset:45056
	v_exp_f32_e32 v144, v96
	v_exp_f32_e32 v145, v97
	v_add_f32_e32 v191, v191, v135
	s_waitcnt lgkmcnt(7)
	v_mfma_f32_32x32x16_bf16 v[66:81], v[212:215], v[122:125], v[66:81]
	ds_read_b128 v[186:189], v228 offset:16384
	v_exp_f32_e32 v238, v98
	v_exp_f32_e32 v239, v99
	v_cvt_pk_bf16_f32 v116, v134, v135
	s_waitcnt lgkmcnt(7)
	v_mfma_f32_32x32x16_bf16 v[50:65], v[216:219], v[122:125], v[50:65]
	ds_read_b128 v[200:203], v229 offset:16384
	v_exp_f32_e32 v240, v100
	v_exp_f32_e32 v241, v101
	v_add_f32_e32 v190, v190, v136
	s_waitcnt lgkmcnt(7)
	v_mfma_f32_32x32x16_bf16 v[34:49], v[220:223], v[122:125], v[34:49]
	ds_read_b128 v[204:207], v230 offset:16384
	v_exp_f32_e32 v242, v102
	v_exp_f32_e32 v243, v103
	v_add_f32_e32 v191, v191, v137
	s_waitcnt lgkmcnt(7)
	v_mfma_f32_32x32x16_bf16 v[18:33], v[224:227], v[122:125], v[18:33]
	ds_read_b128 v[208:211], v231 offset:16384
	v_exp_f32_e32 v244, v104
	v_exp_f32_e32 v245, v105
	v_cvt_pk_bf16_f32 v117, v136, v137
	s_waitcnt lgkmcnt(7)
	v_mfma_f32_32x32x16_bf16 v[66:81], v[166:169], v[126:129], v[66:81]
	ds_read_b128 v[212:215], v228 offset:24576
	v_exp_f32_e32 v130, v106
	v_exp_f32_e32 v131, v107
	v_add_f32_e32 v190, v190, v138
	s_waitcnt lgkmcnt(7)
	v_mfma_f32_32x32x16_bf16 v[50:65], v[170:173], v[126:129], v[50:65]
	ds_read_b128 v[216:219], v229 offset:24576
	v_exp_f32_e32 v132, v108
	v_exp_f32_e32 v133, v109
	v_add_f32_e32 v191, v191, v139
	s_waitcnt lgkmcnt(7)
	v_mfma_f32_32x32x16_bf16 v[34:49], v[178:181], v[126:129], v[34:49]
	ds_read_b128 v[220:223], v230 offset:24576
	v_exp_f32_e32 v134, v110
	v_exp_f32_e32 v135, v111
	v_add_f32_e32 v190, v190, v140
	s_waitcnt lgkmcnt(7)
	v_mfma_f32_32x32x16_bf16 v[18:33], v[182:185], v[126:129], v[18:33]
	ds_read_b128 v[224:227], v231 offset:24576
	v_exp_f32_e32 v136, v112
	v_exp_f32_e32 v137, v113
	v_add_f32_e32 v191, v191, v141
	s_waitcnt lgkmcnt(7)
	v_mfma_f32_32x32x16_bf16 v[82:97], v[186:189], v[158:161], v[0:15]
	ds_read_b128 v[166:169], v232 offset:0
	v_cvt_pk_bf16_f32 v118, v138, v139
	v_cvt_pk_bf16_f32 v119, v140, v141
	v_add_f32_e32 v190, v190, v142
	v_add_f32_e32 v191, v191, v143
	s_waitcnt lgkmcnt(7)
	v_mfma_f32_32x32x16_bf16 v[82:97], v[200:203], v[154:157], v[82:97]
	ds_read_b128 v[170:173], v232 offset:4096
	v_cvt_pk_bf16_f32 v120, v142, v143
	v_add_f32_e32 v190, v190, v144
	v_add_f32_e32 v191, v191, v145
	v_cvt_pk_bf16_f32 v121, v144, v145
	s_waitcnt lgkmcnt(7)
	v_mfma_f32_32x32x16_bf16 v[82:97], v[204:207], v[150:153], v[82:97]
	ds_read_b128 v[178:181], v232 offset:8192
	v_add_f32_e32 v190, v190, v238
	v_add_f32_e32 v191, v191, v239
	v_cvt_pk_bf16_f32 v122, v238, v239
	v_add_f32_e32 v190, v190, v240
	s_waitcnt lgkmcnt(7)
	v_mfma_f32_32x32x16_bf16 v[82:97], v[208:211], v[146:149], v[82:97]
	ds_read_b128 v[182:185], v232 offset:12288
	v_add_f32_e32 v191, v191, v241
	v_cvt_pk_bf16_f32 v123, v240, v241
	v_add_f32_e32 v190, v190, v242
	v_add_f32_e32 v191, v191, v243
	s_waitcnt lgkmcnt(7)
	v_mfma_f32_32x32x16_bf16 v[98:113], v[212:215], v[158:161], v[0:15]
	ds_read_b128 v[186:189], v233 offset:0
	v_cvt_pk_bf16_f32 v124, v242, v243
	v_add_f32_e32 v190, v190, v244
	v_add_f32_e32 v191, v191, v245
	v_cvt_pk_bf16_f32 v125, v244, v245
	s_waitcnt lgkmcnt(7)
	v_mfma_f32_32x32x16_bf16 v[98:113], v[216:219], v[154:157], v[98:113]
	ds_read_b128 v[200:203], v233 offset:4096
	v_add_f32_e32 v190, v190, v130
	v_add_f32_e32 v191, v191, v131
	v_cvt_pk_bf16_f32 v126, v130, v131
	v_add_f32_e32 v190, v190, v132
	s_waitcnt lgkmcnt(7)
	v_mfma_f32_32x32x16_bf16 v[98:113], v[220:223], v[150:153], v[98:113]
	ds_read_b128 v[204:207], v233 offset:8192
	v_add_f32_e32 v191, v191, v133
	v_cvt_pk_bf16_f32 v127, v132, v133
	v_add_f32_e32 v190, v190, v134
	v_add_f32_e32 v191, v191, v135
	s_waitcnt lgkmcnt(7)
	v_mfma_f32_32x32x16_bf16 v[98:113], v[224:227], v[146:149], v[98:113]
	ds_read_b128 v[208:211], v233 offset:12288
	v_cvt_pk_bf16_f32 v128, v134, v135
	v_add_f32_e32 v190, v190, v136
	v_add_f32_e32 v191, v191, v137
	v_cvt_pk_bf16_f32 v129, v136, v137
	s_waitcnt vmcnt(0)
	s_barrier
; template <int MODE> __device__ __forceinline__ void diff_attn_item(const bf16* __restrict__ Qb, const bf16* __restrict__ Kh, const bf16* __restrict__ Vh, ...
;     ...
;   for (int j = 0; j < NTL; ++j) {
;     const bool has1 = (j + 1 < NTL), has2 = (j + 2 < NTL);
;     if (has2 && MODE == 0) SLOADW(s_wr, (j + 2) * KVBLK);
;     bf16x8 f0, f1, f2, f3;
;     if (has1) qkt(pn0, pn1, lds + s_nxt * SHM_BUF + SHM_KV, qr, r32, hi, map, negM);
;     sm_half<MODE>(pc0, lsum, f0, f1);
;     const char* vt = lds + s_cur * SHM_BUF;
;     pv_b128(o, vt + voff[0], f0); pv_b128(o, vt + voff[1], f1);
;     sm_half<MODE>(pc1, lsum, f2, f3);
;     pv_b128(o, vt + voff[2], f2); pv_b128(o, vt + voff[3], f3);
;     asm volatile("s_waitcnt vmcnt(0)" ::: "memory");
;     __syncthreads();
;     pc0 = pn0; pc1 = pn1;
;     const int t = s_cur; s_cur = s_nxt; s_nxt = s_wr; s_wr = t;
	s_waitcnt lgkmcnt(7)
	v_mfma_f32_32x32x16_bf16 v[66:81], v[166:169], v[114:117], v[66:81]
	s_add_u32 m0, s14, 0x8000
	ds_read_b128 v[212:215], v234 offset:0
	global_load_lds_dwordx4 v246, s[10:11]
	v_exp_f32_e32 v130, v82
	v_exp_f32_e32 v131, v83
	v_add_f32_e32 v190, v190, v130
	s_waitcnt lgkmcnt(7)
	v_mfma_f32_32x32x16_bf16 v[50:65], v[170:173], v[114:117], v[50:65]
	s_add_u32 m0, s14, 0xa000
	ds_read_b128 v[216:219], v234 offset:4096
	global_load_lds_dwordx4 v247, s[10:11]
	s_add_u32 s10, s10, 0x4000
	s_addc_u32 s11, s11, 0
	v_exp_f32_e32 v132, v84
	v_exp_f32_e32 v133, v85
	v_add_f32_e32 v191, v191, v131
	s_waitcnt lgkmcnt(7)
	v_mfma_f32_32x32x16_bf16 v[34:49], v[178:181], v[114:117], v[34:49]
	ds_read_b128 v[220:223], v234 offset:8192
	v_exp_f32_e32 v134, v86
	v_exp_f32_e32 v135, v87
	v_add_f32_e32 v190, v190, v132
	s_waitcnt lgkmcnt(7)
	v_mfma_f32_32x32x16_bf16 v[18:33], v[182:185], v[114:117], v[18:33]
	ds_read_b128 v[224:227], v234 offset:12288
	v_exp_f32_e32 v136, v88
	v_exp_f32_e32 v137, v89
	v_add_f32_e32 v191, v191, v133
	s_waitcnt lgkmcnt(7)
	v_mfma_f32_32x32x16_bf16 v[66:81], v[186:189], v[118:121], v[66:81]
	ds_read_b128 v[166:169], v235 offset:0
	v_exp_f32_e32 v138, v90
	v_exp_f32_e32 v139, v91
	v_cvt_pk_bf16_f32 v114, v130, v131
	s_waitcnt lgkmcnt(7)
	v_mfma_f32_32x32x16_bf16 v[50:65], v[200:203], v[118:121], v[50:65]
	ds_read_b128 v[170:173], v235 offset:4096
	v_exp_f32_e32 v140, v92
	v_exp_f32_e32 v141, v93
	v_cvt_pk_bf16_f32 v115, v132, v133
	s_waitcnt lgkmcnt(7)
	v_mfma_f32_32x32x16_bf16 v[34:49], v[204:207], v[118:121], v[34:49]
	ds_read_b128 v[178:181], v235 offset:8192
	v_exp_f32_e32 v142, v94
	v_exp_f32_e32 v143, v95
	v_add_f32_e32 v190, v190, v134
	s_waitcnt lgkmcnt(7)
	v_mfma_f32_32x32x16_bf16 v[18:33], v[208:211], v[118:121], v[18:33]
	ds_read_b128 v[182:185], v235 offset:12288
	v_exp_f32_e32 v144, v96
	v_exp_f32_e32 v145, v97
	v_add_f32_e32 v191, v191, v135
	s_waitcnt lgkmcnt(7)
	v_mfma_f32_32x32x16_bf16 v[66:81], v[212:215], v[122:125], v[66:81]
	ds_read_b128 v[186:189], v228 offset:32768
	v_exp_f32_e32 v238, v98
	v_exp_f32_e32 v239, v99
	v_cvt_pk_bf16_f32 v116, v134, v135
	s_waitcnt lgkmcnt(7)
	v_mfma_f32_32x32x16_bf16 v[50:65], v[216:219], v[122:125], v[50:65]
	ds_read_b128 v[200:203], v229 offset:32768
	v_exp_f32_e32 v240, v100
	v_exp_f32_e32 v241, v101
	v_add_f32_e32 v190, v190, v136
	s_waitcnt lgkmcnt(7)
	v_mfma_f32_32x32x16_bf16 v[34:49], v[220:223], v[122:125], v[34:49]
	ds_read_b128 v[204:207], v230 offset:32768
	v_exp_f32_e32 v242, v102
	v_exp_f32_e32 v243, v103
	v_add_f32_e32 v191, v191, v137
	s_waitcnt lgkmcnt(7)
	v_mfma_f32_32x32x16_bf16 v[18:33], v[224:227], v[122:125], v[18:33]
	ds_read_b128 v[208:211], v231 offset:32768
	v_exp_f32_e32 v244, v104
	v_exp_f32_e32 v245, v105
	v_cvt_pk_bf16_f32 v117, v136, v137
	s_waitcnt lgkmcnt(7)
	v_mfma_f32_32x32x16_bf16 v[66:81], v[166:169], v[126:129], v[66:81]
	ds_read_b128 v[212:215], v228 offset:40960
	v_exp_f32_e32 v130, v106
	v_exp_f32_e32 v131, v107
	v_add_f32_e32 v190, v190, v138
	s_waitcnt lgkmcnt(7)
	v_mfma_f32_32x32x16_bf16 v[50:65], v[170:173], v[126:129], v[50:65]
	ds_read_b128 v[216:219], v229 offset:40960
	v_exp_f32_e32 v132, v108
	v_exp_f32_e32 v133, v109
	v_add_f32_e32 v191, v191, v139
	s_waitcnt lgkmcnt(7)
	v_mfma_f32_32x32x16_bf16 v[34:49], v[178:181], v[126:129], v[34:49]
	ds_read_b128 v[220:223], v230 offset:40960
	v_exp_f32_e32 v134, v110
	v_exp_f32_e32 v135, v111
	v_add_f32_e32 v190, v190, v140
	s_waitcnt lgkmcnt(7)
	v_mfma_f32_32x32x16_bf16 v[18:33], v[182:185], v[126:129], v[18:33]
	ds_read_b128 v[224:227], v231 offset:40960
	v_exp_f32_e32 v136, v112
	v_exp_f32_e32 v137, v113
	v_add_f32_e32 v191, v191, v141
	s_waitcnt lgkmcnt(7)
	v_mfma_f32_32x32x16_bf16 v[82:97], v[186:189], v[158:161], v[0:15]
	ds_read_b128 v[166:169], v232 offset:16384
	v_cvt_pk_bf16_f32 v118, v138, v139
	v_cvt_pk_bf16_f32 v119, v140, v141
	v_add_f32_e32 v190, v190, v142
	v_add_f32_e32 v191, v191, v143
	s_waitcnt lgkmcnt(7)
	v_mfma_f32_32x32x16_bf16 v[82:97], v[200:203], v[154:157], v[82:97]
	ds_read_b128 v[170:173], v232 offset:20480
	v_cvt_pk_bf16_f32 v120, v142, v143
	v_add_f32_e32 v190, v190, v144
	v_add_f32_e32 v191, v191, v145
	v_cvt_pk_bf16_f32 v121, v144, v145
	s_waitcnt lgkmcnt(7)
	v_mfma_f32_32x32x16_bf16 v[82:97], v[204:207], v[150:153], v[82:97]
	ds_read_b128 v[178:181], v232 offset:24576
	v_add_f32_e32 v190, v190, v238
	v_add_f32_e32 v191, v191, v239
	v_cvt_pk_bf16_f32 v122, v238, v239
	v_add_f32_e32 v190, v190, v240
	s_waitcnt lgkmcnt(7)
	v_mfma_f32_32x32x16_bf16 v[82:97], v[208:211], v[146:149], v[82:97]
	ds_read_b128 v[182:185], v232 offset:28672
	v_add_f32_e32 v191, v191, v241
	v_cvt_pk_bf16_f32 v123, v240, v241
	v_add_f32_e32 v190, v190, v242
	v_add_f32_e32 v191, v191, v243
	s_waitcnt lgkmcnt(7)
	v_mfma_f32_32x32x16_bf16 v[98:113], v[212:215], v[158:161], v[0:15]
	ds_read_b128 v[186:189], v233 offset:16384
	v_cvt_pk_bf16_f32 v124, v242, v243
	v_add_f32_e32 v190, v190, v244
	v_add_f32_e32 v191, v191, v245
	v_cvt_pk_bf16_f32 v125, v244, v245
	s_waitcnt lgkmcnt(7)
	v_mfma_f32_32x32x16_bf16 v[98:113], v[216:219], v[154:157], v[98:113]
	ds_read_b128 v[200:203], v233 offset:20480
	v_add_f32_e32 v190, v190, v130
	v_add_f32_e32 v191, v191, v131
	v_cvt_pk_bf16_f32 v126, v130, v131
	v_add_f32_e32 v190, v190, v132
	s_waitcnt lgkmcnt(7)
	v_mfma_f32_32x32x16_bf16 v[98:113], v[220:223], v[150:153], v[98:113]
	ds_read_b128 v[204:207], v233 offset:24576
	v_add_f32_e32 v191, v191, v133
	v_cvt_pk_bf16_f32 v127, v132, v133
	v_add_f32_e32 v190, v190, v134
	v_add_f32_e32 v191, v191, v135
	s_waitcnt lgkmcnt(7)
	v_mfma_f32_32x32x16_bf16 v[98:113], v[224:227], v[146:149], v[98:113]
	ds_read_b128 v[208:211], v233 offset:28672
	v_cvt_pk_bf16_f32 v128, v134, v135
	v_add_f32_e32 v190, v190, v136
	v_add_f32_e32 v191, v191, v137
	v_cvt_pk_bf16_f32 v129, v136, v137
	s_waitcnt vmcnt(0)
	s_barrier
; template <int MODE> __device__ __forceinline__ void sm_half(f32x16& p, float& lsum, bf16x8& f0, bf16x8& f1) {
;   if (MODE != 3) {
; #pragma unroll
;   for (int r = 0; r < 16; ++r) p[r] = __builtin_amdgcn_exp2f(p[r]);
;   }
;   float s0 = 0, s1 = 0;
; #pragma unroll
;   for (int r = 0; r < 16; r += 2) { s0 += p[r]; s1 += p[r + 1]; }
;   lsum += s0 + s1;
;   u32x4 w0 = {cvtpk(p[0], p[1]), cvtpk(p[2], p[3]), cvtpk(p[4], p[5]), cvtpk(p[6], p[7])};
;   u32x4 w1 = {cvtpk(p[8], p[9]), cvtpk(p[10], p[11]), cvtpk(p[12], p[13]), cvtpk(p[14], p[15])};
;   f0 = *reinterpret_cast<bf16x8*>(&w0); f1 = *reinterpret_cast<bf16x8*>(&w1);
; }
; template <int MODE> __device__ __forceinline__ void diff_attn_item(const bf16* __restrict__ Qb, const bf16* __restrict__ Kh, const bf16* __restrict__ Vh, ...
;     ...
;   for (int j = 0; j < NTL; ++j) {
;     const bool has1 = (j + 1 < NTL), has2 = (j + 2 < NTL);
;     if (has2 && MODE == 0) SLOADW(s_wr, (j + 2) * KVBLK);
;     bf16x8 f0, f1, f2, f3;
;     if (has1) qkt(pn0, pn1, lds + s_nxt * SHM_BUF + SHM_KV, qr, r32, hi, map, negM);
;     sm_half<MODE>(pc0, lsum, f0, f1);
;     const char* vt = lds + s_cur * SHM_BUF;
;     pv_b128(o, vt + voff[0], f0); pv_b128(o, vt + voff[1], f1);
;     sm_half<MODE>(pc1, lsum, f2, f3);
;     pv_b128(o, vt + voff[2], f2); pv_b128(o, vt + voff[3], f3);
;     asm volatile("s_waitcnt vmcnt(0)" ::: "memory");
;     __syncthreads();
;     pc0 = pn0; pc1 = pn1;
;     const int t = s_cur; s_cur = s_nxt; s_nxt = s_wr; s_wr = t;
;   }
;   lsum += __shfl_xor(lsum, 32);
	s_waitcnt lgkmcnt(7)
	v_mfma_f32_32x32x16_bf16 v[66:81], v[166:169], v[114:117], v[66:81]
	ds_read_b128 v[212:215], v234 offset:16384
	v_exp_f32_e32 v130, v82
	v_exp_f32_e32 v131, v83
	v_add_f32_e32 v190, v190, v130
	s_waitcnt lgkmcnt(7)
	v_mfma_f32_32x32x16_bf16 v[50:65], v[170:173], v[114:117], v[50:65]
	ds_read_b128 v[216:219], v234 offset:20480
	v_exp_f32_e32 v132, v84
	v_exp_f32_e32 v133, v85
	v_add_f32_e32 v191, v191, v131
	s_waitcnt lgkmcnt(7)
	v_mfma_f32_32x32x16_bf16 v[34:49], v[178:181], v[114:117], v[34:49]
	ds_read_b128 v[220:223], v234 offset:24576
	v_exp_f32_e32 v134, v86
	v_exp_f32_e32 v135, v87
	v_add_f32_e32 v190, v190, v132
	s_waitcnt lgkmcnt(7)
	v_mfma_f32_32x32x16_bf16 v[18:33], v[182:185], v[114:117], v[18:33]
	ds_read_b128 v[224:227], v234 offset:28672
	v_exp_f32_e32 v136, v88
	v_exp_f32_e32 v137, v89
	v_add_f32_e32 v191, v191, v133
	s_waitcnt lgkmcnt(7)
	v_mfma_f32_32x32x16_bf16 v[66:81], v[186:189], v[118:121], v[66:81]
	ds_read_b128 v[166:169], v235 offset:16384
	v_exp_f32_e32 v138, v90
	v_exp_f32_e32 v139, v91
	v_cvt_pk_bf16_f32 v114, v130, v131
	s_waitcnt lgkmcnt(7)
	v_mfma_f32_32x32x16_bf16 v[50:65], v[200:203], v[118:121], v[50:65]
	ds_read_b128 v[170:173], v235 offset:20480
	v_exp_f32_e32 v140, v92
	v_exp_f32_e32 v141, v93
	v_cvt_pk_bf16_f32 v115, v132, v133
	s_waitcnt lgkmcnt(7)
	v_mfma_f32_32x32x16_bf16 v[34:49], v[204:207], v[118:121], v[34:49]
	ds_read_b128 v[178:181], v235 offset:24576
	v_exp_f32_e32 v142, v94
	v_exp_f32_e32 v143, v95
	v_add_f32_e32 v190, v190, v134
	s_waitcnt lgkmcnt(7)
	v_mfma_f32_32x32x16_bf16 v[18:33], v[208:211], v[118:121], v[18:33]
	ds_read_b128 v[182:185], v235 offset:28672
	v_exp_f32_e32 v144, v96
	v_exp_f32_e32 v145, v97
	v_add_f32_e32 v191, v191, v135
	s_waitcnt lgkmcnt(7)
	v_mfma_f32_32x32x16_bf16 v[66:81], v[212:215], v[122:125], v[66:81]
	ds_read_b128 v[186:189], v233 offset:32768
	v_exp_f32_e32 v238, v98
	v_exp_f32_e32 v239, v99
	v_cvt_pk_bf16_f32 v116, v134, v135
	s_waitcnt lgkmcnt(7)
	v_mfma_f32_32x32x16_bf16 v[50:65], v[216:219], v[122:125], v[50:65]
	ds_read_b128 v[200:203], v233 offset:36864
	v_exp_f32_e32 v240, v100
	v_exp_f32_e32 v241, v101
	v_add_f32_e32 v190, v190, v136
	s_waitcnt lgkmcnt(7)
	v_mfma_f32_32x32x16_bf16 v[34:49], v[220:223], v[122:125], v[34:49]
	ds_read_b128 v[204:207], v233 offset:40960
	v_exp_f32_e32 v242, v102
	v_exp_f32_e32 v243, v103
	v_add_f32_e32 v191, v191, v137
	s_waitcnt lgkmcnt(7)
	v_mfma_f32_32x32x16_bf16 v[18:33], v[224:227], v[122:125], v[18:33]
	ds_read_b128 v[208:211], v233 offset:45056
	v_exp_f32_e32 v244, v104
	v_exp_f32_e32 v245, v105
	v_cvt_pk_bf16_f32 v117, v136, v137
	s_waitcnt lgkmcnt(7)
	v_mfma_f32_32x32x16_bf16 v[66:81], v[166:169], v[126:129], v[66:81]
	ds_read_b128 v[166:169], v232 offset:32768
	v_exp_f32_e32 v130, v106
	v_exp_f32_e32 v131, v107
	v_add_f32_e32 v190, v190, v138
	s_waitcnt lgkmcnt(7)
	v_mfma_f32_32x32x16_bf16 v[50:65], v[170:173], v[126:129], v[50:65]
	ds_read_b128 v[170:173], v232 offset:36864
	v_exp_f32_e32 v132, v108
	v_exp_f32_e32 v133, v109
	v_add_f32_e32 v191, v191, v139
	s_waitcnt lgkmcnt(7)
	v_mfma_f32_32x32x16_bf16 v[34:49], v[178:181], v[126:129], v[34:49]
	ds_read_b128 v[178:181], v232 offset:40960
	v_exp_f32_e32 v134, v110
	v_exp_f32_e32 v135, v111
	v_add_f32_e32 v190, v190, v140
	s_waitcnt lgkmcnt(7)
	v_mfma_f32_32x32x16_bf16 v[18:33], v[182:185], v[126:129], v[18:33]
	ds_read_b128 v[182:185], v232 offset:45056
	v_exp_f32_e32 v136, v112
	v_exp_f32_e32 v137, v113
	v_add_f32_e32 v191, v191, v141
	v_cvt_pk_bf16_f32 v118, v138, v139
	v_cvt_pk_bf16_f32 v119, v140, v141
	v_add_f32_e32 v190, v190, v142
	v_add_f32_e32 v191, v191, v143
	v_cvt_pk_bf16_f32 v120, v142, v143
	v_add_f32_e32 v190, v190, v144
	v_add_f32_e32 v191, v191, v145
	v_cvt_pk_bf16_f32 v121, v144, v145
	v_add_f32_e32 v190, v190, v238
	v_add_f32_e32 v191, v191, v239
	v_cvt_pk_bf16_f32 v122, v238, v239
	v_add_f32_e32 v190, v190, v240
	v_add_f32_e32 v191, v191, v241
	v_cvt_pk_bf16_f32 v123, v240, v241
	v_add_f32_e32 v190, v190, v242
	v_add_f32_e32 v191, v191, v243
	v_cvt_pk_bf16_f32 v124, v242, v243
	v_add_f32_e32 v190, v190, v244
	v_add_f32_e32 v191, v191, v245
	v_cvt_pk_bf16_f32 v125, v244, v245
	v_add_f32_e32 v190, v190, v130
	v_add_f32_e32 v191, v191, v131
	v_cvt_pk_bf16_f32 v126, v130, v131
	v_add_f32_e32 v190, v190, v132
	v_add_f32_e32 v191, v191, v133
	v_cvt_pk_bf16_f32 v127, v132, v133
	v_add_f32_e32 v190, v190, v134
	v_add_f32_e32 v191, v191, v135
	v_cvt_pk_bf16_f32 v128, v134, v135
	v_add_f32_e32 v190, v190, v136
	v_add_f32_e32 v191, v191, v137
	v_cvt_pk_bf16_f32 v129, v136, v137
	s_waitcnt lgkmcnt(3)
	v_mfma_f32_32x32x16_bf16 v[66:81], v[166:169], v[114:117], v[66:81]
	ds_read_b128 v[212:215], v234 offset:32768
	s_waitcnt lgkmcnt(3)
	v_mfma_f32_32x32x16_bf16 v[50:65], v[170:173], v[114:117], v[50:65]
	ds_read_b128 v[216:219], v234 offset:36864
	s_waitcnt lgkmcnt(3)
	v_mfma_f32_32x32x16_bf16 v[34:49], v[178:181], v[114:117], v[34:49]
	ds_read_b128 v[220:223], v234 offset:40960
	s_waitcnt lgkmcnt(3)
	v_mfma_f32_32x32x16_bf16 v[18:33], v[182:185], v[114:117], v[18:33]
	ds_read_b128 v[224:227], v234 offset:45056
	s_waitcnt lgkmcnt(11)
	v_mfma_f32_32x32x16_bf16 v[66:81], v[186:189], v[118:121], v[66:81]
	ds_read_b128 v[166:169], v235 offset:32768
	s_waitcnt lgkmcnt(11)
	v_mfma_f32_32x32x16_bf16 v[50:65], v[200:203], v[118:121], v[50:65]
	ds_read_b128 v[170:173], v235 offset:36864
	s_waitcnt lgkmcnt(11)
	v_mfma_f32_32x32x16_bf16 v[34:49], v[204:207], v[118:121], v[34:49]
	ds_read_b128 v[178:181], v235 offset:40960
	s_waitcnt lgkmcnt(11)
	v_mfma_f32_32x32x16_bf16 v[18:33], v[208:211], v[118:121], v[18:33]
	ds_read_b128 v[182:185], v235 offset:45056
	s_waitcnt lgkmcnt(7)
	v_mfma_f32_32x32x16_bf16 v[66:81], v[212:215], v[122:125], v[66:81]
	s_waitcnt lgkmcnt(6)
	v_mfma_f32_32x32x16_bf16 v[50:65], v[216:219], v[122:125], v[50:65]
	s_waitcnt lgkmcnt(5)
	v_mfma_f32_32x32x16_bf16 v[34:49], v[220:223], v[122:125], v[34:49]
	s_waitcnt lgkmcnt(4)
	v_mfma_f32_32x32x16_bf16 v[18:33], v[224:227], v[122:125], v[18:33]
	s_waitcnt lgkmcnt(3)
	v_mfma_f32_32x32x16_bf16 v[66:81], v[166:169], v[126:129], v[66:81]
	s_waitcnt lgkmcnt(2)
	v_mfma_f32_32x32x16_bf16 v[50:65], v[170:173], v[126:129], v[50:65]
	s_waitcnt lgkmcnt(1)
	v_mfma_f32_32x32x16_bf16 v[34:49], v[178:181], v[126:129], v[34:49]
	s_waitcnt lgkmcnt(0)
	v_mfma_f32_32x32x16_bf16 v[18:33], v[182:185], v[126:129], v[18:33]
	v_add_f32_e32 v98, v190, v191
	v_and_b32_e32 v198, 63, v163
	v_bfe_u32 v252, v163, 5, 1
	v_lshlrev_b32_e32 v164, 3, v252
	s_waitcnt lgkmcnt(0)
	s_barrier
; template <int MODE> __device__ __forceinline__ void diff_attn_item(const bf16* __restrict__ Qb, const bf16* __restrict__ Kh, const bf16* __restrict__ Vh, ...
;     ...
;   lsum += __shfl_xor(lsum, 32);
;   const float rl = 1.f / lsum;
;   float* E = (float*)lds;
;   if (map == 1) {
	v_and_b32_e32 v83, 64, v193
	v_xor_b32_e32 v82, 32, v193
	v_add_u32_e32 v83, 64, v83
	v_cmp_lt_i32_e32 vcc, v82, v83
	s_nop 1
	v_cndmask_b32_e32 v82, v193, v82, vcc
	v_lshlrev_b32_e32 v83, 2, v82
	ds_bpermute_b32 v82, v83, v98
	s_nop 0
	s_waitcnt lgkmcnt(0)
	v_add_f32_e32 v82, v98, v82
	v_div_scale_f32 v84, s[8:9], v82, v82, 1.0
	v_rcp_f32_e32 v85, v84
	s_nop 0
	v_fma_f32 v98, -v84, v85, 1.0
	v_fmac_f32_e32 v85, v98, v85
	v_div_scale_f32 v98, vcc, 1.0, v82, 1.0
	s_nop 0
	v_mul_f32_e32 v90, v98, v85
	v_fma_f32 v91, -v84, v90, v98
	v_fmac_f32_e32 v90, v91, v85
	v_fma_f32 v84, -v84, v90, v98
	v_div_fmas_f32 v84, v84, v85, v90
	v_div_fixup_f32 v82, v84, v82, 1.0
	v_cmp_eq_u32_e32 vcc, 1, v197
	s_nop 0
	s_branch .Lda0_join

; template <int MODE> __device__ __forceinline__ void diff_attn_item(const bf16* __restrict__ Qb, const bf16* __restrict__ Kh, const bf16* __restrict__ Vh, ...
;     ...
;   for (int j = 0; j < NTL; ++j) {
;     const bool has1 = (j + 1 < NTL), has2 = (j + 2 < NTL);
;     if (has2 && MODE == 0) SLOADW(s_wr, (j + 2) * KVBLK);
;     bf16x8 f0, f1, f2, f3;
;     if (has1) qkt(pn0, pn1, lds + s_nxt * SHM_BUF + SHM_KV, qr, r32, hi, map, negM);
;     sm_half<MODE>(pc0, lsum, f0, f1);
;     const char* vt = lds + s_cur * SHM_BUF;
;     pv_b128(o, vt + voff[0], f0); pv_b128(o, vt + voff[1], f1);
;     sm_half<MODE>(pc1, lsum, f2, f3);
;     pv_b128(o, vt + voff[2], f2); pv_b128(o, vt + voff[3], f3);
;     asm volatile("s_waitcnt vmcnt(0)" ::: "memory");
;     __syncthreads();
;     pc0 = pn0; pc1 = pn1;
;     const int t = s_cur; s_cur = s_nxt; s_nxt = s_wr; s_wr = t;
.Lda1_loop:
	s_barrier
	s_waitcnt lgkmcnt(7)
	v_mfma_f32_32x32x16_bf16 v[66:81], v[166:169], v[114:117], v[66:81]
	s_add_u32 m0, s14, 0x8000
	ds_read_b128 v[212:215], v234 offset:0
	global_load_lds_dwordx4 v246, s[10:11]
	v_exp_f32_e32 v130, v82
	v_exp_f32_e32 v131, v83
	v_add_f32_e32 v190, v190, v130
	s_waitcnt lgkmcnt(7)
	v_mfma_f32_32x32x16_bf16 v[50:65], v[170:173], v[114:117], v[50:65]
	s_add_u32 m0, s14, 0xa000
	ds_read_b128 v[216:219], v234 offset:4096
	global_load_lds_dwordx4 v247, s[10:11]
	s_add_u32 s10, s10, 0x4000
	s_addc_u32 s11, s11, 0
	v_exp_f32_e32 v132, v84
	v_exp_f32_e32 v133, v85
	v_add_f32_e32 v191, v191, v131
	s_waitcnt lgkmcnt(7)
	v_mfma_f32_32x32x16_bf16 v[34:49], v[178:181], v[114:117], v[34:49]
	s_add_u32 m0, s14, 0x10000
	ds_read_b128 v[220:223], v234 offset:8192
	global_load_lds_dwordx4 v236, s[8:9]
	v_exp_f32_e32 v134, v86
	v_exp_f32_e32 v135, v87
	v_add_f32_e32 v190, v190, v132
	s_waitcnt lgkmcnt(7)
	v_mfma_f32_32x32x16_bf16 v[18:33], v[182:185], v[114:117], v[18:33]
	s_add_u32 m0, s14, 0x12000
	ds_read_b128 v[224:227], v234 offset:12288
	global_load_lds_dwordx4 v237, s[8:9]
	s_add_u32 s8, s8, 0x4000
	s_addc_u32 s9, s9, 0
	v_exp_f32_e32 v136, v88
	v_exp_f32_e32 v137, v89
	v_add_f32_e32 v191, v191, v133
	s_waitcnt lgkmcnt(7)
	v_mfma_f32_32x32x16_bf16 v[66:81], v[186:189], v[118:121], v[66:81]
	ds_read_b128 v[166:169], v235 offset:0
	v_exp_f32_e32 v138, v90
	v_exp_f32_e32 v139, v91
	v_cvt_pk_bf16_f32 v114, v130, v131
	s_waitcnt lgkmcnt(7)
	v_mfma_f32_32x32x16_bf16 v[50:65], v[200:203], v[118:121], v[50:65]
	ds_read_b128 v[170:173], v235 offset:4096
	v_exp_f32_e32 v140, v92
	v_exp_f32_e32 v141, v93
	v_cvt_pk_bf16_f32 v115, v132, v133
	s_waitcnt lgkmcnt(7)
	v_mfma_f32_32x32x16_bf16 v[34:49], v[204:207], v[118:121], v[34:49]
	ds_read_b128 v[178:181], v235 offset:8192
	v_exp_f32_e32 v142, v94
	v_exp_f32_e32 v143, v95
	v_add_f32_e32 v190, v190, v134
	s_waitcnt lgkmcnt(7)
	v_mfma_f32_32x32x16_bf16 v[18:33], v[208:211], v[118:121], v[18:33]
	ds_read_b128 v[182:185], v235 offset:12288
	v_exp_f32_e32 v144, v96
	v_exp_f32_e32 v145, v97
	v_add_f32_e32 v191, v191, v135
	s_waitcnt lgkmcnt(7)
	v_mfma_f32_32x32x16_bf16 v[66:81], v[212:215], v[122:125], v[66:81]
	ds_read_b128 v[186:189], v228 offset:32768
	v_exp_f32_e32 v238, v98
	v_exp_f32_e32 v239, v99
	v_cvt_pk_bf16_f32 v116, v134, v135
	s_waitcnt lgkmcnt(7)
	v_mfma_f32_32x32x16_bf16 v[50:65], v[216:219], v[122:125], v[50:65]
	ds_read_b128 v[200:203], v229 offset:32768
	v_exp_f32_e32 v240, v100
	v_exp_f32_e32 v241, v101
	v_add_f32_e32 v190, v190, v136
	s_waitcnt lgkmcnt(7)
	v_mfma_f32_32x32x16_bf16 v[34:49], v[220:223], v[122:125], v[34:49]
	ds_read_b128 v[204:207], v230 offset:32768
	v_exp_f32_e32 v242, v102
	v_exp_f32_e32 v243, v103
	v_add_f32_e32 v191, v191, v137
	s_waitcnt lgkmcnt(7)
	v_mfma_f32_32x32x16_bf16 v[18:33], v[224:227], v[122:125], v[18:33]
	ds_read_b128 v[208:211], v231 offset:32768
	v_exp_f32_e32 v244, v104
	v_exp_f32_e32 v245, v105
	v_cvt_pk_bf16_f32 v117, v136, v137
	s_waitcnt lgkmcnt(7)
	v_mfma_f32_32x32x16_bf16 v[66:81], v[166:169], v[126:129], v[66:81]
	ds_read_b128 v[212:215], v228 offset:40960
	v_exp_f32_e32 v130, v106
	v_exp_f32_e32 v131, v107
	v_add_f32_e32 v190, v190, v138
	s_waitcnt lgkmcnt(7)
	v_mfma_f32_32x32x16_bf16 v[50:65], v[170:173], v[126:129], v[50:65]
	ds_read_b128 v[216:219], v229 offset:40960
	v_exp_f32_e32 v132, v108
	v_exp_f32_e32 v133, v109
	v_add_f32_e32 v191, v191, v139
	s_waitcnt lgkmcnt(7)
	v_mfma_f32_32x32x16_bf16 v[34:49], v[178:181], v[126:129], v[34:49]
	ds_read_b128 v[220:223], v230 offset:40960
	v_exp_f32_e32 v134, v110
	v_exp_f32_e32 v135, v111
	v_add_f32_e32 v190, v190, v140
	s_waitcnt lgkmcnt(7)
	v_mfma_f32_32x32x16_bf16 v[18:33], v[182:185], v[126:129], v[18:33]
	ds_read_b128 v[224:227], v231 offset:40960
	v_exp_f32_e32 v136, v112
	v_exp_f32_e32 v137, v113
	v_add_f32_e32 v191, v191, v141
	s_waitcnt lgkmcnt(7)
	v_mfma_f32_32x32x16_bf16 v[82:97], v[186:189], v[158:161], v[0:15]
	ds_read_b128 v[166:169], v232 offset:16384
	v_cvt_pk_bf16_f32 v118, v138, v139
	v_cvt_pk_bf16_f32 v119, v140, v141
	v_add_f32_e32 v190, v190, v142
	v_add_f32_e32 v191, v191, v143
	s_waitcnt lgkmcnt(7)
	v_mfma_f32_32x32x16_bf16 v[82:97], v[200:203], v[154:157], v[82:97]
	ds_read_b128 v[170:173], v232 offset:20480
	v_cvt_pk_bf16_f32 v120, v142, v143
	v_add_f32_e32 v190, v190, v144
	v_add_f32_e32 v191, v191, v145
	v_cvt_pk_bf16_f32 v121, v144, v145
	s_waitcnt lgkmcnt(7)
	v_mfma_f32_32x32x16_bf16 v[82:97], v[204:207], v[150:153], v[82:97]
	ds_read_b128 v[178:181], v232 offset:24576
	v_add_f32_e32 v190, v190, v238
	v_add_f32_e32 v191, v191, v239
	v_cvt_pk_bf16_f32 v122, v238, v239
	v_add_f32_e32 v190, v190, v240
	s_waitcnt lgkmcnt(7)
	v_mfma_f32_32x32x16_bf16 v[82:97], v[208:211], v[146:149], v[82:97]
	ds_read_b128 v[182:185], v232 offset:28672
	v_add_f32_e32 v191, v191, v241
	v_cvt_pk_bf16_f32 v123, v240, v241
	v_add_f32_e32 v190, v190, v242
	v_add_f32_e32 v191, v191, v243
	s_waitcnt lgkmcnt(7)
	v_mfma_f32_32x32x16_bf16 v[98:113], v[212:215], v[158:161], v[0:15]
	ds_read_b128 v[186:189], v233 offset:16384
	v_cvt_pk_bf16_f32 v124, v242, v243
	v_add_f32_e32 v190, v190, v244
	v_add_f32_e32 v191, v191, v245
	v_cvt_pk_bf16_f32 v125, v244, v245
	s_waitcnt lgkmcnt(7)
	v_mfma_f32_32x32x16_bf16 v[98:113], v[216:219], v[154:157], v[98:113]
	ds_read_b128 v[200:203], v233 offset:20480
	v_add_f32_e32 v190, v190, v130
	v_add_f32_e32 v191, v191, v131
	v_cvt_pk_bf16_f32 v126, v130, v131
	v_add_f32_e32 v190, v190, v132
	s_waitcnt lgkmcnt(7)
	v_mfma_f32_32x32x16_bf16 v[98:113], v[220:223], v[150:153], v[98:113]
	ds_read_b128 v[204:207], v233 offset:24576
	v_add_f32_e32 v191, v191, v133
	v_cvt_pk_bf16_f32 v127, v132, v133
	v_add_f32_e32 v190, v190, v134
	v_add_f32_e32 v191, v191, v135
	s_waitcnt lgkmcnt(7)
	v_mfma_f32_32x32x16_bf16 v[98:113], v[224:227], v[146:149], v[98:113]
	ds_read_b128 v[208:211], v233 offset:28672
	v_cvt_pk_bf16_f32 v128, v134, v135
	v_add_f32_e32 v190, v190, v136
	v_add_f32_e32 v191, v191, v137
	v_cvt_pk_bf16_f32 v129, v136, v137
	s_waitcnt vmcnt(2)
	s_barrier
; template <int MODE> __device__ __forceinline__ void diff_attn_item(const bf16* __restrict__ Qb, const bf16* __restrict__ Kh, const bf16* __restrict__ Vh, ...
;     ...
;   for (int j = 0; j < NTL; ++j) {
;     const bool has1 = (j + 1 < NTL), has2 = (j + 2 < NTL);
;     if (has2 && MODE == 0) SLOADW(s_wr, (j + 2) * KVBLK);
;     bf16x8 f0, f1, f2, f3;
;     if (has1) qkt(pn0, pn1, lds + s_nxt * SHM_BUF + SHM_KV, qr, r32, hi, map, negM);
;     sm_half<MODE>(pc0, lsum, f0, f1);
;     const char* vt = lds + s_cur * SHM_BUF;
;     pv_b128(o, vt + voff[0], f0); pv_b128(o, vt + voff[1], f1);
;     sm_half<MODE>(pc1, lsum, f2, f3);
;     pv_b128(o, vt + voff[2], f2); pv_b128(o, vt + voff[3], f3);
;     asm volatile("s_waitcnt vmcnt(0)" ::: "memory");
;     __syncthreads();
;     pc0 = pn0; pc1 = pn1;
;     const int t = s_cur; s_cur = s_nxt; s_nxt = s_wr; s_wr = t;
	s_waitcnt lgkmcnt(7)
	v_mfma_f32_32x32x16_bf16 v[66:81], v[166:169], v[114:117], v[66:81]
	s_mov_b32 m0, s14
	ds_read_b128 v[212:215], v234 offset:16384
	global_load_lds_dwordx4 v246, s[10:11]
	v_exp_f32_e32 v130, v82
	v_exp_f32_e32 v131, v83
	v_add_f32_e32 v190, v190, v130
	s_waitcnt lgkmcnt(7)
	v_mfma_f32_32x32x16_bf16 v[50:65], v[170:173], v[114:117], v[50:65]
	s_add_u32 m0, s14, 0x2000
	ds_read_b128 v[216:219], v234 offset:20480
	global_load_lds_dwordx4 v247, s[10:11]
	s_add_u32 s10, s10, 0x4000
	s_addc_u32 s11, s11, 0
	v_exp_f32_e32 v132, v84
	v_exp_f32_e32 v133, v85
	v_add_f32_e32 v191, v191, v131
	s_waitcnt lgkmcnt(7)
	v_mfma_f32_32x32x16_bf16 v[34:49], v[178:181], v[114:117], v[34:49]
	s_add_u32 m0, s14, 0x14000
	ds_read_b128 v[220:223], v234 offset:24576
	global_load_lds_dwordx4 v236, s[8:9]
	v_exp_f32_e32 v134, v86
	v_exp_f32_e32 v135, v87
	v_add_f32_e32 v190, v190, v132
	s_waitcnt lgkmcnt(7)
	v_mfma_f32_32x32x16_bf16 v[18:33], v[182:185], v[114:117], v[18:33]
	s_add_u32 m0, s14, 0x16000
	ds_read_b128 v[224:227], v234 offset:28672
	global_load_lds_dwordx4 v237, s[8:9]
	s_add_u32 s8, s8, 0x4000
	s_addc_u32 s9, s9, 0
	v_exp_f32_e32 v136, v88
	v_exp_f32_e32 v137, v89
	v_add_f32_e32 v191, v191, v133
	s_waitcnt lgkmcnt(7)
	v_mfma_f32_32x32x16_bf16 v[66:81], v[186:189], v[118:121], v[66:81]
	ds_read_b128 v[166:169], v235 offset:16384
	v_exp_f32_e32 v138, v90
	v_exp_f32_e32 v139, v91
	v_cvt_pk_bf16_f32 v114, v130, v131
	s_waitcnt lgkmcnt(7)
	v_mfma_f32_32x32x16_bf16 v[50:65], v[200:203], v[118:121], v[50:65]
	ds_read_b128 v[170:173], v235 offset:20480
	v_exp_f32_e32 v140, v92
	v_exp_f32_e32 v141, v93
	v_cvt_pk_bf16_f32 v115, v132, v133
	s_waitcnt lgkmcnt(7)
	v_mfma_f32_32x32x16_bf16 v[34:49], v[204:207], v[118:121], v[34:49]
	ds_read_b128 v[178:181], v235 offset:24576
	v_exp_f32_e32 v142, v94
	v_exp_f32_e32 v143, v95
	v_add_f32_e32 v190, v190, v134
	s_waitcnt lgkmcnt(7)
	v_mfma_f32_32x32x16_bf16 v[18:33], v[208:211], v[118:121], v[18:33]
	ds_read_b128 v[182:185], v235 offset:28672
	v_exp_f32_e32 v144, v96
	v_exp_f32_e32 v145, v97
	v_add_f32_e32 v191, v191, v135
	s_waitcnt lgkmcnt(7)
	v_mfma_f32_32x32x16_bf16 v[66:81], v[212:215], v[122:125], v[66:81]
	ds_read_b128 v[186:189], v228 offset:0
	v_exp_f32_e32 v238, v98
	v_exp_f32_e32 v239, v99
	v_cvt_pk_bf16_f32 v116, v134, v135
	s_waitcnt lgkmcnt(7)
	v_mfma_f32_32x32x16_bf16 v[50:65], v[216:219], v[122:125], v[50:65]
	ds_read_b128 v[200:203], v229 offset:0
	v_exp_f32_e32 v240, v100
	v_exp_f32_e32 v241, v101
	v_add_f32_e32 v190, v190, v136
	s_waitcnt lgkmcnt(7)
	v_mfma_f32_32x32x16_bf16 v[34:49], v[220:223], v[122:125], v[34:49]
	ds_read_b128 v[204:207], v230 offset:0
	v_exp_f32_e32 v242, v102
	v_exp_f32_e32 v243, v103
	v_add_f32_e32 v191, v191, v137
	s_waitcnt lgkmcnt(7)
	v_mfma_f32_32x32x16_bf16 v[18:33], v[224:227], v[122:125], v[18:33]
	ds_read_b128 v[208:211], v231 offset:0
	v_exp_f32_e32 v244, v104
	v_exp_f32_e32 v245, v105
	v_cvt_pk_bf16_f32 v117, v136, v137
	s_waitcnt lgkmcnt(7)
	v_mfma_f32_32x32x16_bf16 v[66:81], v[166:169], v[126:129], v[66:81]
	ds_read_b128 v[212:215], v228 offset:8192
	v_exp_f32_e32 v130, v106
	v_exp_f32_e32 v131, v107
	v_add_f32_e32 v190, v190, v138
	s_waitcnt lgkmcnt(7)
	v_mfma_f32_32x32x16_bf16 v[50:65], v[170:173], v[126:129], v[50:65]
	ds_read_b128 v[216:219], v229 offset:8192
	v_exp_f32_e32 v132, v108
	v_exp_f32_e32 v133, v109
	v_add_f32_e32 v191, v191, v139
	s_waitcnt lgkmcnt(7)
	v_mfma_f32_32x32x16_bf16 v[34:49], v[178:181], v[126:129], v[34:49]
	ds_read_b128 v[220:223], v230 offset:8192
	v_exp_f32_e32 v134, v110
	v_exp_f32_e32 v135, v111
	v_add_f32_e32 v190, v190, v140
	s_waitcnt lgkmcnt(7)
	v_mfma_f32_32x32x16_bf16 v[18:33], v[182:185], v[126:129], v[18:33]
	ds_read_b128 v[224:227], v231 offset:8192
	v_exp_f32_e32 v136, v112
	v_exp_f32_e32 v137, v113
	v_add_f32_e32 v191, v191, v141
	s_waitcnt lgkmcnt(7)
	v_mfma_f32_32x32x16_bf16 v[82:97], v[186:189], v[158:161], v[0:15]
	ds_read_b128 v[166:169], v232 offset:32768
	v_cvt_pk_bf16_f32 v118, v138, v139
	v_cvt_pk_bf16_f32 v119, v140, v141
	v_add_f32_e32 v190, v190, v142
	v_add_f32_e32 v191, v191, v143
	s_waitcnt lgkmcnt(7)
	v_mfma_f32_32x32x16_bf16 v[82:97], v[200:203], v[154:157], v[82:97]
	ds_read_b128 v[170:173], v232 offset:36864
	v_cvt_pk_bf16_f32 v120, v142, v143
	v_add_f32_e32 v190, v190, v144
	v_add_f32_e32 v191, v191, v145
	v_cvt_pk_bf16_f32 v121, v144, v145
	s_waitcnt lgkmcnt(7)
	v_mfma_f32_32x32x16_bf16 v[82:97], v[204:207], v[150:153], v[82:97]
	ds_read_b128 v[178:181], v232 offset:40960
	v_add_f32_e32 v190, v190, v238
	v_add_f32_e32 v191, v191, v239
	v_cvt_pk_bf16_f32 v122, v238, v239
	v_add_f32_e32 v190, v190, v240
	s_waitcnt lgkmcnt(7)
	v_mfma_f32_32x32x16_bf16 v[82:97], v[208:211], v[146:149], v[82:97]
	ds_read_b128 v[182:185], v232 offset:45056
	v_add_f32_e32 v191, v191, v241
	v_cvt_pk_bf16_f32 v123, v240, v241
	v_add_f32_e32 v190, v190, v242
	v_add_f32_e32 v191, v191, v243
	s_waitcnt lgkmcnt(7)
	v_mfma_f32_32x32x16_bf16 v[98:113], v[212:215], v[158:161], v[0:15]
	ds_read_b128 v[186:189], v233 offset:32768
	v_cvt_pk_bf16_f32 v124, v242, v243
	v_add_f32_e32 v190, v190, v244
	v_add_f32_e32 v191, v191, v245
	v_cvt_pk_bf16_f32 v125, v244, v245
	s_waitcnt lgkmcnt(7)
	v_mfma_f32_32x32x16_bf16 v[98:113], v[216:219], v[154:157], v[98:113]
	ds_read_b128 v[200:203], v233 offset:36864
	v_add_f32_e32 v190, v190, v130
	v_add_f32_e32 v191, v191, v131
	v_cvt_pk_bf16_f32 v126, v130, v131
	v_add_f32_e32 v190, v190, v132
	s_waitcnt lgkmcnt(7)
	v_mfma_f32_32x32x16_bf16 v[98:113], v[220:223], v[150:153], v[98:113]
	ds_read_b128 v[204:207], v233 offset:40960
	v_add_f32_e32 v191, v191, v133
	v_cvt_pk_bf16_f32 v127, v132, v133
	v_add_f32_e32 v190, v190, v134
	v_add_f32_e32 v191, v191, v135
	s_waitcnt lgkmcnt(7)
	v_mfma_f32_32x32x16_bf16 v[98:113], v[224:227], v[146:149], v[98:113]
	ds_read_b128 v[208:211], v233 offset:45056
	v_cvt_pk_bf16_f32 v128, v134, v135
	v_add_f32_e32 v190, v190, v136
	v_add_f32_e32 v191, v191, v137
	v_cvt_pk_bf16_f32 v129, v136, v137
	s_waitcnt vmcnt(2)
	s_barrier
; template <int MODE> __device__ __forceinline__ void diff_attn_item(const bf16* __restrict__ Qb, const bf16* __restrict__ Kh, const bf16* __restrict__ Vh, ...
;     ...
;   for (int j = 0; j < NTL; ++j) {
;     const bool has1 = (j + 1 < NTL), has2 = (j + 2 < NTL);
;     if (has2 && MODE == 0) SLOADW(s_wr, (j + 2) * KVBLK);
;     bf16x8 f0, f1, f2, f3;
;     if (has1) qkt(pn0, pn1, lds + s_nxt * SHM_BUF + SHM_KV, qr, r32, hi, map, negM);
;     sm_half<MODE>(pc0, lsum, f0, f1);
;     const char* vt = lds + s_cur * SHM_BUF;
;     pv_b128(o, vt + voff[0], f0); pv_b128(o, vt + voff[1], f1);
;     sm_half<MODE>(pc1, lsum, f2, f3);
;     pv_b128(o, vt + voff[2], f2); pv_b128(o, vt + voff[3], f3);
;     asm volatile("s_waitcnt vmcnt(0)" ::: "memory");
;     __syncthreads();
;     pc0 = pn0; pc1 = pn1;
;     const int t = s_cur; s_cur = s_nxt; s_nxt = s_wr; s_wr = t;
	s_waitcnt lgkmcnt(7)
	v_mfma_f32_32x32x16_bf16 v[66:81], v[166:169], v[114:117], v[66:81]
	s_add_u32 m0, s14, 0x4000
	ds_read_b128 v[212:215], v234 offset:32768
	global_load_lds_dwordx4 v246, s[10:11]
	v_exp_f32_e32 v130, v82
	v_exp_f32_e32 v131, v83
	v_add_f32_e32 v190, v190, v130
	s_waitcnt lgkmcnt(7)
	v_mfma_f32_32x32x16_bf16 v[50:65], v[170:173], v[114:117], v[50:65]
	s_add_u32 m0, s14, 0x6000
	ds_read_b128 v[216:219], v234 offset:36864
	global_load_lds_dwordx4 v247, s[10:11]
	s_add_u32 s10, s10, 0x4000
	s_addc_u32 s11, s11, 0
	v_exp_f32_e32 v132, v84
	v_exp_f32_e32 v133, v85
	v_add_f32_e32 v191, v191, v131
	s_waitcnt lgkmcnt(7)
	v_mfma_f32_32x32x16_bf16 v[34:49], v[178:181], v[114:117], v[34:49]
	s_add_u32 m0, s14, 0xc000
	ds_read_b128 v[220:223], v234 offset:40960
	global_load_lds_dwordx4 v236, s[8:9]
	v_exp_f32_e32 v134, v86
	v_exp_f32_e32 v135, v87
	v_add_f32_e32 v190, v190, v132
	s_waitcnt lgkmcnt(7)
	v_mfma_f32_32x32x16_bf16 v[18:33], v[182:185], v[114:117], v[18:33]
	s_add_u32 m0, s14, 0xe000
	ds_read_b128 v[224:227], v234 offset:45056
	global_load_lds_dwordx4 v237, s[8:9]
	s_add_u32 s8, s8, 0x4000
	s_addc_u32 s9, s9, 0
	v_exp_f32_e32 v136, v88
	v_exp_f32_e32 v137, v89
	v_add_f32_e32 v191, v191, v133
	s_waitcnt lgkmcnt(7)
	v_mfma_f32_32x32x16_bf16 v[66:81], v[186:189], v[118:121], v[66:81]
	ds_read_b128 v[166:169], v235 offset:32768
	v_exp_f32_e32 v138, v90
	v_exp_f32_e32 v139, v91
	v_cvt_pk_bf16_f32 v114, v130, v131
	s_waitcnt lgkmcnt(7)
	v_mfma_f32_32x32x16_bf16 v[50:65], v[200:203], v[118:121], v[50:65]
	ds_read_b128 v[170:173], v235 offset:36864
	v_exp_f32_e32 v140, v92
	v_exp_f32_e32 v141, v93
	v_cvt_pk_bf16_f32 v115, v132, v133
	s_waitcnt lgkmcnt(7)
	v_mfma_f32_32x32x16_bf16 v[34:49], v[204:207], v[118:121], v[34:49]
	ds_read_b128 v[178:181], v235 offset:40960
	v_exp_f32_e32 v142, v94
	v_exp_f32_e32 v143, v95
	v_add_f32_e32 v190, v190, v134
	s_waitcnt lgkmcnt(7)
	v_mfma_f32_32x32x16_bf16 v[18:33], v[208:211], v[118:121], v[18:33]
	ds_read_b128 v[182:185], v235 offset:45056
	v_exp_f32_e32 v144, v96
	v_exp_f32_e32 v145, v97
	v_add_f32_e32 v191, v191, v135
	s_waitcnt lgkmcnt(7)
	v_mfma_f32_32x32x16_bf16 v[66:81], v[212:215], v[122:125], v[66:81]
	ds_read_b128 v[186:189], v228 offset:16384
	v_exp_f32_e32 v238, v98
	v_exp_f32_e32 v239, v99
	v_cvt_pk_bf16_f32 v116, v134, v135
	s_waitcnt lgkmcnt(7)
	v_mfma_f32_32x32x16_bf16 v[50:65], v[216:219], v[122:125], v[50:65]
	ds_read_b128 v[200:203], v229 offset:16384
	v_exp_f32_e32 v240, v100
	v_exp_f32_e32 v241, v101
	v_add_f32_e32 v190, v190, v136
	s_waitcnt lgkmcnt(7)
	v_mfma_f32_32x32x16_bf16 v[34:49], v[220:223], v[122:125], v[34:49]
	ds_read_b128 v[204:207], v230 offset:16384
	v_exp_f32_e32 v242, v102
	v_exp_f32_e32 v243, v103
	v_add_f32_e32 v191, v191, v137
	s_waitcnt lgkmcnt(7)
	v_mfma_f32_32x32x16_bf16 v[18:33], v[224:227], v[122:125], v[18:33]
	ds_read_b128 v[208:211], v231 offset:16384
	v_exp_f32_e32 v244, v104
	v_exp_f32_e32 v245, v105
	v_cvt_pk_bf16_f32 v117, v136, v137
	s_waitcnt lgkmcnt(7)
	v_mfma_f32_32x32x16_bf16 v[66:81], v[166:169], v[126:129], v[66:81]
	ds_read_b128 v[212:215], v228 offset:24576
	v_exp_f32_e32 v130, v106
	v_exp_f32_e32 v131, v107
	v_add_f32_e32 v190, v190, v138
	s_waitcnt lgkmcnt(7)
	v_mfma_f32_32x32x16_bf16 v[50:65], v[170:173], v[126:129], v[50:65]
	ds_read_b128 v[216:219], v229 offset:24576
	v_exp_f32_e32 v132, v108
	v_exp_f32_e32 v133, v109
	v_add_f32_e32 v191, v191, v139
	s_waitcnt lgkmcnt(7)
	v_mfma_f32_32x32x16_bf16 v[34:49], v[178:181], v[126:129], v[34:49]
	ds_read_b128 v[220:223], v230 offset:24576
	v_exp_f32_e32 v134, v110
	v_exp_f32_e32 v135, v111
	v_add_f32_e32 v190, v190, v140
	s_waitcnt lgkmcnt(7)
	v_mfma_f32_32x32x16_bf16 v[18:33], v[182:185], v[126:129], v[18:33]
	ds_read_b128 v[224:227], v231 offset:24576
	v_exp_f32_e32 v136, v112
	v_exp_f32_e32 v137, v113
	v_add_f32_e32 v191, v191, v141
	s_waitcnt lgkmcnt(7)
	v_mfma_f32_32x32x16_bf16 v[82:97], v[186:189], v[158:161], v[0:15]
	ds_read_b128 v[166:169], v232 offset:0
	v_cvt_pk_bf16_f32 v118, v138, v139
	v_cvt_pk_bf16_f32 v119, v140, v141
	v_add_f32_e32 v190, v190, v142
	v_add_f32_e32 v191, v191, v143
	s_waitcnt lgkmcnt(7)
	v_mfma_f32_32x32x16_bf16 v[82:97], v[200:203], v[154:157], v[82:97]
	ds_read_b128 v[170:173], v232 offset:4096
	v_cvt_pk_bf16_f32 v120, v142, v143
	v_add_f32_e32 v190, v190, v144
	v_add_f32_e32 v191, v191, v145
	v_cvt_pk_bf16_f32 v121, v144, v145
	s_waitcnt lgkmcnt(7)
	v_mfma_f32_32x32x16_bf16 v[82:97], v[204:207], v[150:153], v[82:97]
	ds_read_b128 v[178:181], v232 offset:8192
	v_add_f32_e32 v190, v190, v238
	v_add_f32_e32 v191, v191, v239
	v_cvt_pk_bf16_f32 v122, v238, v239
	v_add_f32_e32 v190, v190, v240
	s_waitcnt lgkmcnt(7)
	v_mfma_f32_32x32x16_bf16 v[82:97], v[208:211], v[146:149], v[82:97]
	ds_read_b128 v[182:185], v232 offset:12288
	v_add_f32_e32 v191, v191, v241
	v_cvt_pk_bf16_f32 v123, v240, v241
	v_add_f32_e32 v190, v190, v242
	v_add_f32_e32 v191, v191, v243
	s_waitcnt lgkmcnt(7)
	v_mfma_f32_32x32x16_bf16 v[98:113], v[212:215], v[158:161], v[0:15]
	ds_read_b128 v[186:189], v233 offset:0
	v_cvt_pk_bf16_f32 v124, v242, v243
	v_add_f32_e32 v190, v190, v244
	v_add_f32_e32 v191, v191, v245
	v_cvt_pk_bf16_f32 v125, v244, v245
	s_waitcnt lgkmcnt(7)
	v_mfma_f32_32x32x16_bf16 v[98:113], v[216:219], v[154:157], v[98:113]
	ds_read_b128 v[200:203], v233 offset:4096
	v_add_f32_e32 v190, v190, v130
	v_add_f32_e32 v191, v191, v131
	v_cvt_pk_bf16_f32 v126, v130, v131
	v_add_f32_e32 v190, v190, v132
	s_waitcnt lgkmcnt(7)
	v_mfma_f32_32x32x16_bf16 v[98:113], v[220:223], v[150:153], v[98:113]
	ds_read_b128 v[204:207], v233 offset:8192
	v_add_f32_e32 v191, v191, v133
	v_cvt_pk_bf16_f32 v127, v132, v133
	v_add_f32_e32 v190, v190, v134
	v_add_f32_e32 v191, v191, v135
	s_waitcnt lgkmcnt(7)
	v_mfma_f32_32x32x16_bf16 v[98:113], v[224:227], v[146:149], v[98:113]
	ds_read_b128 v[208:211], v233 offset:12288
	v_cvt_pk_bf16_f32 v128, v134, v135
	v_add_f32_e32 v190, v190, v136
	v_add_f32_e32 v191, v191, v137
	v_cvt_pk_bf16_f32 v129, v136, v137
	s_waitcnt vmcnt(2)
	s_sub_u32 s15, s15, 1
	s_cmp_lg_u32 s15, 0
	s_cbranch_scc1 .Lda1_loop
; template <int MODE> __device__ __forceinline__ void diff_attn_item(const bf16* __restrict__ Qb, const bf16* __restrict__ Kh, const bf16* __restrict__ Vh, ...
;     ...
;   for (int j = 0; j < NTL; ++j) {
;     const bool has1 = (j + 1 < NTL), has2 = (j + 2 < NTL);
;     if (has2 && MODE == 0) SLOADW(s_wr, (j + 2) * KVBLK);
;     bf16x8 f0, f1, f2, f3;
;     if (has1) qkt(pn0, pn1, lds + s_nxt * SHM_BUF + SHM_KV, qr, r32, hi, map, negM);
;     sm_half<MODE>(pc0, lsum, f0, f1);
;     const char* vt = lds + s_cur * SHM_BUF;
;     pv_b128(o, vt + voff[0], f0); pv_b128(o, vt + voff[1], f1);
;     sm_half<MODE>(pc1, lsum, f2, f3);
;     pv_b128(o, vt + voff[2], f2); pv_b128(o, vt + voff[3], f3);
;     asm volatile("s_waitcnt vmcnt(0)" ::: "memory");
;     __syncthreads();
;     pc0 = pn0; pc1 = pn1;
;     const int t = s_cur; s_cur = s_nxt; s_nxt = s_wr; s_wr = t;
	s_barrier
	s_waitcnt lgkmcnt(7)
	v_mfma_f32_32x32x16_bf16 v[66:81], v[166:169], v[114:117], v[66:81]
	s_add_u32 m0, s14, 0x8000
	ds_read_b128 v[212:215], v234 offset:0
	global_load_lds_dwordx4 v246, s[10:11]
	v_exp_f32_e32 v130, v82
	v_exp_f32_e32 v131, v83
	v_add_f32_e32 v190, v190, v130
	s_waitcnt lgkmcnt(7)
	v_mfma_f32_32x32x16_bf16 v[50:65], v[170:173], v[114:117], v[50:65]
	s_add_u32 m0, s14, 0xa000
	ds_read_b128 v[216:219], v234 offset:4096
	global_load_lds_dwordx4 v247, s[10:11]
	s_add_u32 s10, s10, 0x4000
	s_addc_u32 s11, s11, 0
	v_exp_f32_e32 v132, v84
	v_exp_f32_e32 v133, v85
	v_add_f32_e32 v191, v191, v131
	s_waitcnt lgkmcnt(7)
	v_mfma_f32_32x32x16_bf16 v[34:49], v[178:181], v[114:117], v[34:49]
	s_add_u32 m0, s14, 0x10000
	ds_read_b128 v[220:223], v234 offset:8192
	global_load_lds_dwordx4 v236, s[8:9]
	v_exp_f32_e32 v134, v86
	v_exp_f32_e32 v135, v87
	v_add_f32_e32 v190, v190, v132
	s_waitcnt lgkmcnt(7)
	v_mfma_f32_32x32x16_bf16 v[18:33], v[182:185], v[114:117], v[18:33]
	s_add_u32 m0, s14, 0x12000
	ds_read_b128 v[224:227], v234 offset:12288
	global_load_lds_dwordx4 v237, s[8:9]
	s_add_u32 s8, s8, 0x4000
	s_addc_u32 s9, s9, 0
	v_exp_f32_e32 v136, v88
	v_exp_f32_e32 v137, v89
	v_add_f32_e32 v191, v191, v133
	s_waitcnt lgkmcnt(7)
	v_mfma_f32_32x32x16_bf16 v[66:81], v[186:189], v[118:121], v[66:81]
	ds_read_b128 v[166:169], v235 offset:0
	v_exp_f32_e32 v138, v90
	v_exp_f32_e32 v139, v91
	v_cvt_pk_bf16_f32 v114, v130, v131
	s_waitcnt lgkmcnt(7)
	v_mfma_f32_32x32x16_bf16 v[50:65], v[200:203], v[118:121], v[50:65]
	ds_read_b128 v[170:173], v235 offset:4096
	v_exp_f32_e32 v140, v92
	v_exp_f32_e32 v141, v93
	v_cvt_pk_bf16_f32 v115, v132, v133
	s_waitcnt lgkmcnt(7)
	v_mfma_f32_32x32x16_bf16 v[34:49], v[204:207], v[118:121], v[34:49]
	ds_read_b128 v[178:181], v235 offset:8192
	v_exp_f32_e32 v142, v94
	v_exp_f32_e32 v143, v95
	v_add_f32_e32 v190, v190, v134
	s_waitcnt lgkmcnt(7)
	v_mfma_f32_32x32x16_bf16 v[18:33], v[208:211], v[118:121], v[18:33]
	ds_read_b128 v[182:185], v235 offset:12288
	v_exp_f32_e32 v144, v96
	v_exp_f32_e32 v145, v97
	v_add_f32_e32 v191, v191, v135
	s_waitcnt lgkmcnt(7)
	v_mfma_f32_32x32x16_bf16 v[66:81], v[212:215], v[122:125], v[66:81]
	ds_read_b128 v[186:189], v228 offset:32768
	v_exp_f32_e32 v238, v98
	v_exp_f32_e32 v239, v99
	v_cvt_pk_bf16_f32 v116, v134, v135
	s_waitcnt lgkmcnt(7)
	v_mfma_f32_32x32x16_bf16 v[50:65], v[216:219], v[122:125], v[50:65]
	ds_read_b128 v[200:203], v229 offset:32768
	v_exp_f32_e32 v240, v100
	v_exp_f32_e32 v241, v101
	v_add_f32_e32 v190, v190, v136
	s_waitcnt lgkmcnt(7)
	v_mfma_f32_32x32x16_bf16 v[34:49], v[220:223], v[122:125], v[34:49]
	ds_read_b128 v[204:207], v230 offset:32768
	v_exp_f32_e32 v242, v102
	v_exp_f32_e32 v243, v103
	v_add_f32_e32 v191, v191, v137
	s_waitcnt lgkmcnt(7)
	v_mfma_f32_32x32x16_bf16 v[18:33], v[224:227], v[122:125], v[18:33]
	ds_read_b128 v[208:211], v231 offset:32768
	v_exp_f32_e32 v244, v104
	v_exp_f32_e32 v245, v105
	v_cvt_pk_bf16_f32 v117, v136, v137
	s_waitcnt lgkmcnt(7)
	v_mfma_f32_32x32x16_bf16 v[66:81], v[166:169], v[126:129], v[66:81]
	ds_read_b128 v[212:215], v228 offset:40960
	v_exp_f32_e32 v130, v106
	v_exp_f32_e32 v131, v107
	v_add_f32_e32 v190, v190, v138
	s_waitcnt lgkmcnt(7)
	v_mfma_f32_32x32x16_bf16 v[50:65], v[170:173], v[126:129], v[50:65]
	ds_read_b128 v[216:219], v229 offset:40960
	v_exp_f32_e32 v132, v108
	v_exp_f32_e32 v133, v109
	v_add_f32_e32 v191, v191, v139
	s_waitcnt lgkmcnt(7)
	v_mfma_f32_32x32x16_bf16 v[34:49], v[178:181], v[126:129], v[34:49]
	ds_read_b128 v[220:223], v230 offset:40960
	v_exp_f32_e32 v134, v110
	v_exp_f32_e32 v135, v111
	v_add_f32_e32 v190, v190, v140
	s_waitcnt lgkmcnt(7)
	v_mfma_f32_32x32x16_bf16 v[18:33], v[182:185], v[126:129], v[18:33]
	ds_read_b128 v[224:227], v231 offset:40960
	v_exp_f32_e32 v136, v112
	v_exp_f32_e32 v137, v113
	v_add_f32_e32 v191, v191, v141
	s_waitcnt lgkmcnt(7)
	v_mfma_f32_32x32x16_bf16 v[82:97], v[186:189], v[158:161], v[0:15]
	ds_read_b128 v[166:169], v232 offset:16384
	v_cvt_pk_bf16_f32 v118, v138, v139
	v_cvt_pk_bf16_f32 v119, v140, v141
	v_add_f32_e32 v190, v190, v142
	v_add_f32_e32 v191, v191, v143
	s_waitcnt lgkmcnt(7)
	v_mfma_f32_32x32x16_bf16 v[82:97], v[200:203], v[154:157], v[82:97]
	ds_read_b128 v[170:173], v232 offset:20480
	v_cvt_pk_bf16_f32 v120, v142, v143
	v_add_f32_e32 v190, v190, v144
	v_add_f32_e32 v191, v191, v145
	v_cvt_pk_bf16_f32 v121, v144, v145
	s_waitcnt lgkmcnt(7)
	v_mfma_f32_32x32x16_bf16 v[82:97], v[204:207], v[150:153], v[82:97]
	ds_read_b128 v[178:181], v232 offset:24576
	v_add_f32_e32 v190, v190, v238
	v_add_f32_e32 v191, v191, v239
	v_cvt_pk_bf16_f32 v122, v238, v239
	v_add_f32_e32 v190, v190, v240
	s_waitcnt lgkmcnt(7)
	v_mfma_f32_32x32x16_bf16 v[82:97], v[208:211], v[146:149], v[82:97]
	ds_read_b128 v[182:185], v232 offset:28672
	v_add_f32_e32 v191, v191, v241
	v_cvt_pk_bf16_f32 v123, v240, v241
	v_add_f32_e32 v190, v190, v242
	v_add_f32_e32 v191, v191, v243
	s_waitcnt lgkmcnt(7)
	v_mfma_f32_32x32x16_bf16 v[98:113], v[212:215], v[158:161], v[0:15]
	ds_read_b128 v[186:189], v233 offset:16384
	v_cvt_pk_bf16_f32 v124, v242, v243
	v_add_f32_e32 v190, v190, v244
	v_add_f32_e32 v191, v191, v245
	v_cvt_pk_bf16_f32 v125, v244, v245
	s_waitcnt lgkmcnt(7)
	v_mfma_f32_32x32x16_bf16 v[98:113], v[216:219], v[154:157], v[98:113]
	ds_read_b128 v[200:203], v233 offset:20480
	v_add_f32_e32 v190, v190, v130
	v_add_f32_e32 v191, v191, v131
	v_cvt_pk_bf16_f32 v126, v130, v131
	v_add_f32_e32 v190, v190, v132
	s_waitcnt lgkmcnt(7)
	v_mfma_f32_32x32x16_bf16 v[98:113], v[220:223], v[150:153], v[98:113]
	ds_read_b128 v[204:207], v233 offset:24576
	v_add_f32_e32 v191, v191, v133
	v_cvt_pk_bf16_f32 v127, v132, v133
	v_add_f32_e32 v190, v190, v134
	v_add_f32_e32 v191, v191, v135
	s_waitcnt lgkmcnt(7)
	v_mfma_f32_32x32x16_bf16 v[98:113], v[224:227], v[146:149], v[98:113]
	ds_read_b128 v[208:211], v233 offset:28672
	v_cvt_pk_bf16_f32 v128, v134, v135
	v_add_f32_e32 v190, v190, v136
	v_add_f32_e32 v191, v191, v137
	v_cvt_pk_bf16_f32 v129, v136, v137
	s_waitcnt vmcnt(2)
	s_barrier
; template <int MODE> __device__ __forceinline__ void diff_attn_item(const bf16* __restrict__ Qb, const bf16* __restrict__ Kh, const bf16* __restrict__ Vh, ...
;     ...
;   for (int j = 0; j < NTL; ++j) {
;     const bool has1 = (j + 1 < NTL), has2 = (j + 2 < NTL);
;     if (has2 && MODE == 0) SLOADW(s_wr, (j + 2) * KVBLK);
;     bf16x8 f0, f1, f2, f3;
;     if (has1) qkt(pn0, pn1, lds + s_nxt * SHM_BUF + SHM_KV, qr, r32, hi, map, negM);
;     sm_half<MODE>(pc0, lsum, f0, f1);
;     const char* vt = lds + s_cur * SHM_BUF;
;     pv_b128(o, vt + voff[0], f0); pv_b128(o, vt + voff[1], f1);
;     sm_half<MODE>(pc1, lsum, f2, f3);
;     pv_b128(o, vt + voff[2], f2); pv_b128(o, vt + voff[3], f3);
;     asm volatile("s_waitcnt vmcnt(0)" ::: "memory");
;     __syncthreads();
;     pc0 = pn0; pc1 = pn1;
;     const int t = s_cur; s_cur = s_nxt; s_nxt = s_wr; s_wr = t;
	s_waitcnt lgkmcnt(7)
	v_mfma_f32_32x32x16_bf16 v[66:81], v[166:169], v[114:117], v[66:81]
	s_mov_b32 m0, s14
	ds_read_b128 v[212:215], v234 offset:16384
	global_load_lds_dwordx4 v246, s[10:11]
	v_exp_f32_e32 v130, v82
	v_exp_f32_e32 v131, v83
	v_add_f32_e32 v190, v190, v130
	s_waitcnt lgkmcnt(7)
	v_mfma_f32_32x32x16_bf16 v[50:65], v[170:173], v[114:117], v[50:65]
	s_add_u32 m0, s14, 0x2000
	ds_read_b128 v[216:219], v234 offset:20480
	global_load_lds_dwordx4 v247, s[10:11]
	s_add_u32 s10, s10, 0x4000
	s_addc_u32 s11, s11, 0
	v_exp_f32_e32 v132, v84
	v_exp_f32_e32 v133, v85
	v_add_f32_e32 v191, v191, v131
	s_waitcnt lgkmcnt(7)
	v_mfma_f32_32x32x16_bf16 v[34:49], v[178:181], v[114:117], v[34:49]
	s_add_u32 m0, s14, 0x14000
	ds_read_b128 v[220:223], v234 offset:24576
	global_load_lds_dwordx4 v236, s[8:9]
	v_exp_f32_e32 v134, v86
	v_exp_f32_e32 v135, v87
	v_add_f32_e32 v190, v190, v132
	s_waitcnt lgkmcnt(7)
	v_mfma_f32_32x32x16_bf16 v[18:33], v[182:185], v[114:117], v[18:33]
	s_add_u32 m0, s14, 0x16000
	ds_read_b128 v[224:227], v234 offset:28672
	global_load_lds_dwordx4 v237, s[8:9]
	s_add_u32 s8, s8, 0x4000
	s_addc_u32 s9, s9, 0
	v_exp_f32_e32 v136, v88
	v_exp_f32_e32 v137, v89
	v_add_f32_e32 v191, v191, v133
	s_waitcnt lgkmcnt(7)
	v_mfma_f32_32x32x16_bf16 v[66:81], v[186:189], v[118:121], v[66:81]
	ds_read_b128 v[166:169], v235 offset:16384
	v_exp_f32_e32 v138, v90
	v_exp_f32_e32 v139, v91
	v_cvt_pk_bf16_f32 v114, v130, v131
	s_waitcnt lgkmcnt(7)
	v_mfma_f32_32x32x16_bf16 v[50:65], v[200:203], v[118:121], v[50:65]
	ds_read_b128 v[170:173], v235 offset:20480
	v_exp_f32_e32 v140, v92
	v_exp_f32_e32 v141, v93
	v_cvt_pk_bf16_f32 v115, v132, v133
	s_waitcnt lgkmcnt(7)
	v_mfma_f32_32x32x16_bf16 v[34:49], v[204:207], v[118:121], v[34:49]
	ds_read_b128 v[178:181], v235 offset:24576
	v_exp_f32_e32 v142, v94
	v_exp_f32_e32 v143, v95
	v_add_f32_e32 v190, v190, v134
	s_waitcnt lgkmcnt(7)
	v_mfma_f32_32x32x16_bf16 v[18:33], v[208:211], v[118:121], v[18:33]
	ds_read_b128 v[182:185], v235 offset:28672
	v_exp_f32_e32 v144, v96
	v_exp_f32_e32 v145, v97
	v_add_f32_e32 v191, v191, v135
	s_waitcnt lgkmcnt(7)
	v_mfma_f32_32x32x16_bf16 v[66:81], v[212:215], v[122:125], v[66:81]
	ds_read_b128 v[186:189], v228 offset:0
	v_exp_f32_e32 v238, v98
	v_exp_f32_e32 v239, v99
	v_cvt_pk_bf16_f32 v116, v134, v135
	s_waitcnt lgkmcnt(7)
	v_mfma_f32_32x32x16_bf16 v[50:65], v[216:219], v[122:125], v[50:65]
	ds_read_b128 v[200:203], v229 offset:0
	v_exp_f32_e32 v240, v100
	v_exp_f32_e32 v241, v101
	v_add_f32_e32 v190, v190, v136
	s_waitcnt lgkmcnt(7)
	v_mfma_f32_32x32x16_bf16 v[34:49], v[220:223], v[122:125], v[34:49]
	ds_read_b128 v[204:207], v230 offset:0
	v_exp_f32_e32 v242, v102
	v_exp_f32_e32 v243, v103
	v_add_f32_e32 v191, v191, v137
	s_waitcnt lgkmcnt(7)
	v_mfma_f32_32x32x16_bf16 v[18:33], v[224:227], v[122:125], v[18:33]
	ds_read_b128 v[208:211], v231 offset:0
	v_exp_f32_e32 v244, v104
	v_exp_f32_e32 v245, v105
	v_cvt_pk_bf16_f32 v117, v136, v137
	s_waitcnt lgkmcnt(7)
	v_mfma_f32_32x32x16_bf16 v[66:81], v[166:169], v[126:129], v[66:81]
	ds_read_b128 v[212:215], v228 offset:8192
	v_exp_f32_e32 v130, v106
	v_exp_f32_e32 v131, v107
	v_add_f32_e32 v190, v190, v138
	s_waitcnt lgkmcnt(7)
	v_mfma_f32_32x32x16_bf16 v[50:65], v[170:173], v[126:129], v[50:65]
	ds_read_b128 v[216:219], v229 offset:8192
	v_exp_f32_e32 v132, v108
	v_exp_f32_e32 v133, v109
	v_add_f32_e32 v191, v191, v139
	s_waitcnt lgkmcnt(7)
	v_mfma_f32_32x32x16_bf16 v[34:49], v[178:181], v[126:129], v[34:49]
	ds_read_b128 v[220:223], v230 offset:8192
	v_exp_f32_e32 v134, v110
	v_exp_f32_e32 v135, v111
	v_add_f32_e32 v190, v190, v140
	s_waitcnt lgkmcnt(7)
	v_mfma_f32_32x32x16_bf16 v[18:33], v[182:185], v[126:129], v[18:33]
	ds_read_b128 v[224:227], v231 offset:8192
	v_exp_f32_e32 v136, v112
	v_exp_f32_e32 v137, v113
	v_add_f32_e32 v191, v191, v141
	s_waitcnt lgkmcnt(7)
	v_mfma_f32_32x32x16_bf16 v[82:97], v[186:189], v[158:161], v[0:15]
	ds_read_b128 v[166:169], v232 offset:32768
	v_cvt_pk_bf16_f32 v118, v138, v139
	v_cvt_pk_bf16_f32 v119, v140, v141
	v_add_f32_e32 v190, v190, v142
	v_add_f32_e32 v191, v191, v143
	s_waitcnt lgkmcnt(7)
	v_mfma_f32_32x32x16_bf16 v[82:97], v[200:203], v[154:157], v[82:97]
	ds_read_b128 v[170:173], v232 offset:36864
	v_cvt_pk_bf16_f32 v120, v142, v143
	v_add_f32_e32 v190, v190, v144
	v_add_f32_e32 v191, v191, v145
	v_cvt_pk_bf16_f32 v121, v144, v145
	s_waitcnt lgkmcnt(7)
	v_mfma_f32_32x32x16_bf16 v[82:97], v[204:207], v[150:153], v[82:97]
	ds_read_b128 v[178:181], v232 offset:40960
	v_add_f32_e32 v190, v190, v238
	v_add_f32_e32 v191, v191, v239
	v_cvt_pk_bf16_f32 v122, v238, v239
	v_add_f32_e32 v190, v190, v240
	s_waitcnt lgkmcnt(7)
	v_mfma_f32_32x32x16_bf16 v[82:97], v[208:211], v[146:149], v[82:97]
	ds_read_b128 v[182:185], v232 offset:45056
	v_add_f32_e32 v191, v191, v241
	v_cvt_pk_bf16_f32 v123, v240, v241
	v_add_f32_e32 v190, v190, v242
	v_add_f32_e32 v191, v191, v243
	s_waitcnt lgkmcnt(7)
	v_mfma_f32_32x32x16_bf16 v[98:113], v[212:215], v[158:161], v[0:15]
	ds_read_b128 v[186:189], v233 offset:32768
	v_cvt_pk_bf16_f32 v124, v242, v243
	v_add_f32_e32 v190, v190, v244
	v_add_f32_e32 v191, v191, v245
	v_cvt_pk_bf16_f32 v125, v244, v245
	s_waitcnt lgkmcnt(7)
	v_mfma_f32_32x32x16_bf16 v[98:113], v[216:219], v[154:157], v[98:113]
	ds_read_b128 v[200:203], v233 offset:36864
	v_add_f32_e32 v190, v190, v130
	v_add_f32_e32 v191, v191, v131
	v_cvt_pk_bf16_f32 v126, v130, v131
	v_add_f32_e32 v190, v190, v132
	s_waitcnt lgkmcnt(7)
	v_mfma_f32_32x32x16_bf16 v[98:113], v[220:223], v[150:153], v[98:113]
	ds_read_b128 v[204:207], v233 offset:40960
	v_add_f32_e32 v191, v191, v133
	v_cvt_pk_bf16_f32 v127, v132, v133
	v_add_f32_e32 v190, v190, v134
	v_add_f32_e32 v191, v191, v135
	s_waitcnt lgkmcnt(7)
	v_mfma_f32_32x32x16_bf16 v[98:113], v[224:227], v[146:149], v[98:113]
	ds_read_b128 v[208:211], v233 offset:45056
	v_cvt_pk_bf16_f32 v128, v134, v135
	v_add_f32_e32 v190, v190, v136
	v_add_f32_e32 v191, v191, v137
	v_cvt_pk_bf16_f32 v129, v136, v137
	s_waitcnt vmcnt(2)
	s_barrier
; template <int MODE> __device__ __forceinline__ void diff_attn_item(const bf16* __restrict__ Qb, const bf16* __restrict__ Kh, const bf16* __restrict__ Vh, ...
;     ...
;   for (int j = 0; j < NTL; ++j) {
;     const bool has1 = (j + 1 < NTL), has2 = (j + 2 < NTL);
;     if (has2 && MODE == 0) SLOADW(s_wr, (j + 2) * KVBLK);
;     bf16x8 f0, f1, f2, f3;
;     if (has1) qkt(pn0, pn1, lds + s_nxt * SHM_BUF + SHM_KV, qr, r32, hi, map, negM);
;     sm_half<MODE>(pc0, lsum, f0, f1);
;     const char* vt = lds + s_cur * SHM_BUF;
;     pv_b128(o, vt + voff[0], f0); pv_b128(o, vt + voff[1], f1);
;     sm_half<MODE>(pc1, lsum, f2, f3);
;     pv_b128(o, vt + voff[2], f2); pv_b128(o, vt + voff[3], f3);
;     asm volatile("s_waitcnt vmcnt(0)" ::: "memory");
;     __syncthreads();
;     pc0 = pn0; pc1 = pn1;
;     const int t = s_cur; s_cur = s_nxt; s_nxt = s_wr; s_wr = t;
	s_waitcnt lgkmcnt(7)
	v_mfma_f32_32x32x16_bf16 v[66:81], v[166:169], v[114:117], v[66:81]
	s_add_u32 m0, s14, 0x4000
	ds_read_b128 v[212:215], v234 offset:32768
	global_load_lds_dwordx4 v246, s[10:11]
	v_exp_f32_e32 v130, v82
	v_exp_f32_e32 v131, v83
	v_add_f32_e32 v190, v190, v130
	s_waitcnt lgkmcnt(7)
	v_mfma_f32_32x32x16_bf16 v[50:65], v[170:173], v[114:117], v[50:65]
	s_add_u32 m0, s14, 0x6000
	ds_read_b128 v[216:219], v234 offset:36864
	global_load_lds_dwordx4 v247, s[10:11]
	s_add_u32 s10, s10, 0x4000
	s_addc_u32 s11, s11, 0
	v_exp_f32_e32 v132, v84
	v_exp_f32_e32 v133, v85
	v_add_f32_e32 v191, v191, v131
	s_waitcnt lgkmcnt(7)
	v_mfma_f32_32x32x16_bf16 v[34:49], v[178:181], v[114:117], v[34:49]
	ds_read_b128 v[220:223], v234 offset:40960
	v_exp_f32_e32 v134, v86
	v_exp_f32_e32 v135, v87
	v_add_f32_e32 v190, v190, v132
	s_waitcnt lgkmcnt(7)
	v_mfma_f32_32x32x16_bf16 v[18:33], v[182:185], v[114:117], v[18:33]
	ds_read_b128 v[224:227], v234 offset:45056
	v_exp_f32_e32 v136, v88
	v_exp_f32_e32 v137, v89
	v_add_f32_e32 v191, v191, v133
	s_waitcnt lgkmcnt(7)
	v_mfma_f32_32x32x16_bf16 v[66:81], v[186:189], v[118:121], v[66:81]
	ds_read_b128 v[166:169], v235 offset:32768
	v_exp_f32_e32 v138, v90
	v_exp_f32_e32 v139, v91
	v_cvt_pk_bf16_f32 v114, v130, v131
	s_waitcnt lgkmcnt(7)
	v_mfma_f32_32x32x16_bf16 v[50:65], v[200:203], v[118:121], v[50:65]
	ds_read_b128 v[170:173], v235 offset:36864
	v_exp_f32_e32 v140, v92
	v_exp_f32_e32 v141, v93
	v_cvt_pk_bf16_f32 v115, v132, v133
	s_waitcnt lgkmcnt(7)
	v_mfma_f32_32x32x16_bf16 v[34:49], v[204:207], v[118:121], v[34:49]
	ds_read_b128 v[178:181], v235 offset:40960
	v_exp_f32_e32 v142, v94
	v_exp_f32_e32 v143, v95
	v_add_f32_e32 v190, v190, v134
	s_waitcnt lgkmcnt(7)
	v_mfma_f32_32x32x16_bf16 v[18:33], v[208:211], v[118:121], v[18:33]
	ds_read_b128 v[182:185], v235 offset:45056
	v_exp_f32_e32 v144, v96
	v_exp_f32_e32 v145, v97
	v_add_f32_e32 v191, v191, v135
	s_waitcnt lgkmcnt(7)
	v_mfma_f32_32x32x16_bf16 v[66:81], v[212:215], v[122:125], v[66:81]
	ds_read_b128 v[186:189], v228 offset:16384
	v_exp_f32_e32 v238, v98
	v_exp_f32_e32 v239, v99
	v_cvt_pk_bf16_f32 v116, v134, v135
	s_waitcnt lgkmcnt(7)
	v_mfma_f32_32x32x16_bf16 v[50:65], v[216:219], v[122:125], v[50:65]
	ds_read_b128 v[200:203], v229 offset:16384
	v_exp_f32_e32 v240, v100
	v_exp_f32_e32 v241, v101
	v_add_f32_e32 v190, v190, v136
	s_waitcnt lgkmcnt(7)
	v_mfma_f32_32x32x16_bf16 v[34:49], v[220:223], v[122:125], v[34:49]
	ds_read_b128 v[204:207], v230 offset:16384
	v_exp_f32_e32 v242, v102
	v_exp_f32_e32 v243, v103
	v_add_f32_e32 v191, v191, v137
	s_waitcnt lgkmcnt(7)
	v_mfma_f32_32x32x16_bf16 v[18:33], v[224:227], v[122:125], v[18:33]
	ds_read_b128 v[208:211], v231 offset:16384
	v_exp_f32_e32 v244, v104
	v_exp_f32_e32 v245, v105
	v_cvt_pk_bf16_f32 v117, v136, v137
	s_waitcnt lgkmcnt(7)
	v_mfma_f32_32x32x16_bf16 v[66:81], v[166:169], v[126:129], v[66:81]
	ds_read_b128 v[212:215], v228 offset:24576
	v_exp_f32_e32 v130, v106
	v_exp_f32_e32 v131, v107
	v_add_f32_e32 v190, v190, v138
	s_waitcnt lgkmcnt(7)
	v_mfma_f32_32x32x16_bf16 v[50:65], v[170:173], v[126:129], v[50:65]
	ds_read_b128 v[216:219], v229 offset:24576
	v_exp_f32_e32 v132, v108
	v_exp_f32_e32 v133, v109
	v_add_f32_e32 v191, v191, v139
	s_waitcnt lgkmcnt(7)
	v_mfma_f32_32x32x16_bf16 v[34:49], v[178:181], v[126:129], v[34:49]
	ds_read_b128 v[220:223], v230 offset:24576
	v_exp_f32_e32 v134, v110
	v_exp_f32_e32 v135, v111
	v_add_f32_e32 v190, v190, v140
	s_waitcnt lgkmcnt(7)
	v_mfma_f32_32x32x16_bf16 v[18:33], v[182:185], v[126:129], v[18:33]
	ds_read_b128 v[224:227], v231 offset:24576
	v_exp_f32_e32 v136, v112
	v_exp_f32_e32 v137, v113
	v_add_f32_e32 v191, v191, v141
	s_waitcnt lgkmcnt(7)
	v_mfma_f32_32x32x16_bf16 v[82:97], v[186:189], v[158:161], v[0:15]
	ds_read_b128 v[166:169], v232 offset:0
	v_cvt_pk_bf16_f32 v118, v138, v139
	v_cvt_pk_bf16_f32 v119, v140, v141
	v_add_f32_e32 v190, v190, v142
	v_add_f32_e32 v191, v191, v143
	s_waitcnt lgkmcnt(7)
	v_mfma_f32_32x32x16_bf16 v[82:97], v[200:203], v[154:157], v[82:97]
	ds_read_b128 v[170:173], v232 offset:4096
	v_cvt_pk_bf16_f32 v120, v142, v143
	v_add_f32_e32 v190, v190, v144
	v_add_f32_e32 v191, v191, v145
	v_cvt_pk_bf16_f32 v121, v144, v145
	s_waitcnt lgkmcnt(7)
	v_mfma_f32_32x32x16_bf16 v[82:97], v[204:207], v[150:153], v[82:97]
	ds_read_b128 v[178:181], v232 offset:8192
	v_add_f32_e32 v190, v190, v238
	v_add_f32_e32 v191, v191, v239
	v_cvt_pk_bf16_f32 v122, v238, v239
	v_add_f32_e32 v190, v190, v240
	s_waitcnt lgkmcnt(7)
	v_mfma_f32_32x32x16_bf16 v[82:97], v[208:211], v[146:149], v[82:97]
	ds_read_b128 v[182:185], v232 offset:12288
	v_add_f32_e32 v191, v191, v241
	v_cvt_pk_bf16_f32 v123, v240, v241
	v_add_f32_e32 v190, v190, v242
	v_add_f32_e32 v191, v191, v243
	s_waitcnt lgkmcnt(7)
	v_mfma_f32_32x32x16_bf16 v[98:113], v[212:215], v[158:161], v[0:15]
	ds_read_b128 v[186:189], v233 offset:0
	v_cvt_pk_bf16_f32 v124, v242, v243
	v_add_f32_e32 v190, v190, v244
	v_add_f32_e32 v191, v191, v245
	v_cvt_pk_bf16_f32 v125, v244, v245
	s_waitcnt lgkmcnt(7)
	v_mfma_f32_32x32x16_bf16 v[98:113], v[216:219], v[154:157], v[98:113]
	ds_read_b128 v[200:203], v233 offset:4096
	v_add_f32_e32 v190, v190, v130
	v_add_f32_e32 v191, v191, v131
	v_cvt_pk_bf16_f32 v126, v130, v131
	v_add_f32_e32 v190, v190, v132
	s_waitcnt lgkmcnt(7)
	v_mfma_f32_32x32x16_bf16 v[98:113], v[220:223], v[150:153], v[98:113]
	ds_read_b128 v[204:207], v233 offset:8192
	v_add_f32_e32 v191, v191, v133
	v_cvt_pk_bf16_f32 v127, v132, v133
	v_add_f32_e32 v190, v190, v134
	v_add_f32_e32 v191, v191, v135
	s_waitcnt lgkmcnt(7)
	v_mfma_f32_32x32x16_bf16 v[98:113], v[224:227], v[146:149], v[98:113]
	ds_read_b128 v[208:211], v233 offset:12288
	v_cvt_pk_bf16_f32 v128, v134, v135
	v_add_f32_e32 v190, v190, v136
	v_add_f32_e32 v191, v191, v137
	v_cvt_pk_bf16_f32 v129, v136, v137
	s_waitcnt vmcnt(0)
	s_barrier
; template <int MODE> __device__ __forceinline__ void diff_attn_item(const bf16* __restrict__ Qb, const bf16* __restrict__ Kh, const bf16* __restrict__ Vh, ...
;     ...
;   for (int j = 0; j < NTL; ++j) {
;     const bool has1 = (j + 1 < NTL), has2 = (j + 2 < NTL);
;     if (has2 && MODE == 0) SLOADW(s_wr, (j + 2) * KVBLK);
;     bf16x8 f0, f1, f2, f3;
;     if (has1) qkt(pn0, pn1, lds + s_nxt * SHM_BUF + SHM_KV, qr, r32, hi, map, negM);
;     sm_half<MODE>(pc0, lsum, f0, f1);
;     const char* vt = lds + s_cur * SHM_BUF;
;     pv_b128(o, vt + voff[0], f0); pv_b128(o, vt + voff[1], f1);
;     sm_half<MODE>(pc1, lsum, f2, f3);
;     pv_b128(o, vt + voff[2], f2); pv_b128(o, vt + voff[3], f3);
;     asm volatile("s_waitcnt vmcnt(0)" ::: "memory");
;     __syncthreads();
;     pc0 = pn0; pc1 = pn1;
;     const int t = s_cur; s_cur = s_nxt; s_nxt = s_wr; s_wr = t;
	s_waitcnt lgkmcnt(7)
	v_mfma_f32_32x32x16_bf16 v[66:81], v[166:169], v[114:117], v[66:81]
	s_add_u32 m0, s14, 0x8000
	ds_read_b128 v[212:215], v234 offset:0
	global_load_lds_dwordx4 v246, s[10:11]
	v_exp_f32_e32 v130, v82
	v_exp_f32_e32 v131, v83
	v_add_f32_e32 v190, v190, v130
	s_waitcnt lgkmcnt(7)
	v_mfma_f32_32x32x16_bf16 v[50:65], v[170:173], v[114:117], v[50:65]
	s_add_u32 m0, s14, 0xa000
	ds_read_b128 v[216:219], v234 offset:4096
	global_load_lds_dwordx4 v247, s[10:11]
	s_add_u32 s10, s10, 0x4000
	s_addc_u32 s11, s11, 0
	v_exp_f32_e32 v132, v84
	v_exp_f32_e32 v133, v85
	v_add_f32_e32 v191, v191, v131
	s_waitcnt lgkmcnt(7)
	v_mfma_f32_32x32x16_bf16 v[34:49], v[178:181], v[114:117], v[34:49]
	ds_read_b128 v[220:223], v234 offset:8192
	v_exp_f32_e32 v134, v86
	v_exp_f32_e32 v135, v87
	v_add_f32_e32 v190, v190, v132
	s_waitcnt lgkmcnt(7)
	v_mfma_f32_32x32x16_bf16 v[18:33], v[182:185], v[114:117], v[18:33]
	ds_read_b128 v[224:227], v234 offset:12288
	v_exp_f32_e32 v136, v88
	v_exp_f32_e32 v137, v89
	v_add_f32_e32 v191, v191, v133
	s_waitcnt lgkmcnt(7)
	v_mfma_f32_32x32x16_bf16 v[66:81], v[186:189], v[118:121], v[66:81]
	ds_read_b128 v[166:169], v235 offset:0
	v_exp_f32_e32 v138, v90
	v_exp_f32_e32 v139, v91
	v_cvt_pk_bf16_f32 v114, v130, v131
	s_waitcnt lgkmcnt(7)
	v_mfma_f32_32x32x16_bf16 v[50:65], v[200:203], v[118:121], v[50:65]
	ds_read_b128 v[170:173], v235 offset:4096
	v_exp_f32_e32 v140, v92
	v_exp_f32_e32 v141, v93
	v_cvt_pk_bf16_f32 v115, v132, v133
	s_waitcnt lgkmcnt(7)
	v_mfma_f32_32x32x16_bf16 v[34:49], v[204:207], v[118:121], v[34:49]
	ds_read_b128 v[178:181], v235 offset:8192
	v_exp_f32_e32 v142, v94
	v_exp_f32_e32 v143, v95
	v_add_f32_e32 v190, v190, v134
	s_waitcnt lgkmcnt(7)
	v_mfma_f32_32x32x16_bf16 v[18:33], v[208:211], v[118:121], v[18:33]
	ds_read_b128 v[182:185], v235 offset:12288
	v_exp_f32_e32 v144, v96
	v_exp_f32_e32 v145, v97
	v_add_f32_e32 v191, v191, v135
	s_waitcnt lgkmcnt(7)
	v_mfma_f32_32x32x16_bf16 v[66:81], v[212:215], v[122:125], v[66:81]
	ds_read_b128 v[186:189], v228 offset:32768
	v_exp_f32_e32 v238, v98
	v_exp_f32_e32 v239, v99
	v_cvt_pk_bf16_f32 v116, v134, v135
	s_waitcnt lgkmcnt(7)
	v_mfma_f32_32x32x16_bf16 v[50:65], v[216:219], v[122:125], v[50:65]
	ds_read_b128 v[200:203], v229 offset:32768
	v_exp_f32_e32 v240, v100
	v_exp_f32_e32 v241, v101
	v_add_f32_e32 v190, v190, v136
	s_waitcnt lgkmcnt(7)
	v_mfma_f32_32x32x16_bf16 v[34:49], v[220:223], v[122:125], v[34:49]
	ds_read_b128 v[204:207], v230 offset:32768
	v_exp_f32_e32 v242, v102
	v_exp_f32_e32 v243, v103
	v_add_f32_e32 v191, v191, v137
	s_waitcnt lgkmcnt(7)
	v_mfma_f32_32x32x16_bf16 v[18:33], v[224:227], v[122:125], v[18:33]
	ds_read_b128 v[208:211], v231 offset:32768
	v_exp_f32_e32 v244, v104
	v_exp_f32_e32 v245, v105
	v_cvt_pk_bf16_f32 v117, v136, v137
	s_waitcnt lgkmcnt(7)
	v_mfma_f32_32x32x16_bf16 v[66:81], v[166:169], v[126:129], v[66:81]
	ds_read_b128 v[212:215], v228 offset:40960
	v_exp_f32_e32 v130, v106
	v_exp_f32_e32 v131, v107
	v_add_f32_e32 v190, v190, v138
	s_waitcnt lgkmcnt(7)
	v_mfma_f32_32x32x16_bf16 v[50:65], v[170:173], v[126:129], v[50:65]
	ds_read_b128 v[216:219], v229 offset:40960
	v_exp_f32_e32 v132, v108
	v_exp_f32_e32 v133, v109
	v_add_f32_e32 v191, v191, v139
	s_waitcnt lgkmcnt(7)
	v_mfma_f32_32x32x16_bf16 v[34:49], v[178:181], v[126:129], v[34:49]
	ds_read_b128 v[220:223], v230 offset:40960
	v_exp_f32_e32 v134, v110
	v_exp_f32_e32 v135, v111
	v_add_f32_e32 v190, v190, v140
	s_waitcnt lgkmcnt(7)
	v_mfma_f32_32x32x16_bf16 v[18:33], v[182:185], v[126:129], v[18:33]
	ds_read_b128 v[224:227], v231 offset:40960
	v_exp_f32_e32 v136, v112
	v_exp_f32_e32 v137, v113
	v_add_f32_e32 v191, v191, v141
	s_waitcnt lgkmcnt(7)
	v_mfma_f32_32x32x16_bf16 v[82:97], v[186:189], v[158:161], v[0:15]
	ds_read_b128 v[166:169], v232 offset:16384
	v_cvt_pk_bf16_f32 v118, v138, v139
	v_cvt_pk_bf16_f32 v119, v140, v141
	v_add_f32_e32 v190, v190, v142
	v_add_f32_e32 v191, v191, v143
	s_waitcnt lgkmcnt(7)
	v_mfma_f32_32x32x16_bf16 v[82:97], v[200:203], v[154:157], v[82:97]
	ds_read_b128 v[170:173], v232 offset:20480
	v_cvt_pk_bf16_f32 v120, v142, v143
	v_add_f32_e32 v190, v190, v144
	v_add_f32_e32 v191, v191, v145
	v_cvt_pk_bf16_f32 v121, v144, v145
	s_waitcnt lgkmcnt(7)
	v_mfma_f32_32x32x16_bf16 v[82:97], v[204:207], v[150:153], v[82:97]
	ds_read_b128 v[178:181], v232 offset:24576
	v_add_f32_e32 v190, v190, v238
	v_add_f32_e32 v191, v191, v239
	v_cvt_pk_bf16_f32 v122, v238, v239
	v_add_f32_e32 v190, v190, v240
	s_waitcnt lgkmcnt(7)
	v_mfma_f32_32x32x16_bf16 v[82:97], v[208:211], v[146:149], v[82:97]
	ds_read_b128 v[182:185], v232 offset:28672
	v_add_f32_e32 v191, v191, v241
	v_cvt_pk_bf16_f32 v123, v240, v241
	v_add_f32_e32 v190, v190, v242
	v_add_f32_e32 v191, v191, v243
	s_waitcnt lgkmcnt(7)
	v_mfma_f32_32x32x16_bf16 v[98:113], v[212:215], v[158:161], v[0:15]
	ds_read_b128 v[186:189], v233 offset:16384
	v_cvt_pk_bf16_f32 v124, v242, v243
	v_add_f32_e32 v190, v190, v244
	v_add_f32_e32 v191, v191, v245
	v_cvt_pk_bf16_f32 v125, v244, v245
	s_waitcnt lgkmcnt(7)
	v_mfma_f32_32x32x16_bf16 v[98:113], v[216:219], v[154:157], v[98:113]
	ds_read_b128 v[200:203], v233 offset:20480
	v_add_f32_e32 v190, v190, v130
	v_add_f32_e32 v191, v191, v131
	v_cvt_pk_bf16_f32 v126, v130, v131
	v_add_f32_e32 v190, v190, v132
	s_waitcnt lgkmcnt(7)
	v_mfma_f32_32x32x16_bf16 v[98:113], v[220:223], v[150:153], v[98:113]
	ds_read_b128 v[204:207], v233 offset:24576
	v_add_f32_e32 v191, v191, v133
	v_cvt_pk_bf16_f32 v127, v132, v133
	v_add_f32_e32 v190, v190, v134
	v_add_f32_e32 v191, v191, v135
	s_waitcnt lgkmcnt(7)
	v_mfma_f32_32x32x16_bf16 v[98:113], v[224:227], v[146:149], v[98:113]
	ds_read_b128 v[208:211], v233 offset:28672
	v_cvt_pk_bf16_f32 v128, v134, v135
	v_add_f32_e32 v190, v190, v136
	v_add_f32_e32 v191, v191, v137
	v_cvt_pk_bf16_f32 v129, v136, v137
	s_waitcnt vmcnt(0)
	s_barrier
; template <int MODE> __device__ __forceinline__ void sm_half(f32x16& p, float& lsum, bf16x8& f0, bf16x8& f1) {
;   if (MODE != 3) {
; #pragma unroll
;   for (int r = 0; r < 16; ++r) p[r] = __builtin_amdgcn_exp2f(p[r]);
;   }
;   float s0 = 0, s1 = 0;
; #pragma unroll
;   for (int r = 0; r < 16; r += 2) { s0 += p[r]; s1 += p[r + 1]; }
;   lsum += s0 + s1;
;   u32x4 w0 = {cvtpk(p[0], p[1]), cvtpk(p[2], p[3]), cvtpk(p[4], p[5]), cvtpk(p[6], p[7])};
;   u32x4 w1 = {cvtpk(p[8], p[9]), cvtpk(p[10], p[11]), cvtpk(p[12], p[13]), cvtpk(p[14], p[15])};
;   f0 = *reinterpret_cast<bf16x8*>(&w0); f1 = *reinterpret_cast<bf16x8*>(&w1);
; }
; template <int MODE> __device__ __forceinline__ void diff_attn_item(const bf16* __restrict__ Qb, const bf16* __restrict__ Kh, const bf16* __restrict__ Vh, ...
;     ...
;   for (int j = 0; j < NTL; ++j) {
;     const bool has1 = (j + 1 < NTL), has2 = (j + 2 < NTL);
;     if (has2 && MODE == 0) SLOADW(s_wr, (j + 2) * KVBLK);
;     bf16x8 f0, f1, f2, f3;
;     if (has1) qkt(pn0, pn1, lds + s_nxt * SHM_BUF + SHM_KV, qr, r32, hi, map, negM);
;     sm_half<MODE>(pc0, lsum, f0, f1);
;     const char* vt = lds + s_cur * SHM_BUF;
;     pv_b128(o, vt + voff[0], f0); pv_b128(o, vt + voff[1], f1);
;     sm_half<MODE>(pc1, lsum, f2, f3);
;     pv_b128(o, vt + voff[2], f2); pv_b128(o, vt + voff[3], f3);
;     asm volatile("s_waitcnt vmcnt(0)" ::: "memory");
;     __syncthreads();
;     pc0 = pn0; pc1 = pn1;
;     const int t = s_cur; s_cur = s_nxt; s_nxt = s_wr; s_wr = t;
;   }
;   lsum += __shfl_xor(lsum, 32);
	s_waitcnt lgkmcnt(7)
	v_mfma_f32_32x32x16_bf16 v[66:81], v[166:169], v[114:117], v[66:81]
	ds_read_b128 v[212:215], v234 offset:16384
	v_exp_f32_e32 v130, v82
	v_exp_f32_e32 v131, v83
	v_add_f32_e32 v190, v190, v130
	s_waitcnt lgkmcnt(7)
	v_mfma_f32_32x32x16_bf16 v[50:65], v[170:173], v[114:117], v[50:65]
	ds_read_b128 v[216:219], v234 offset:20480
	v_exp_f32_e32 v132, v84
	v_exp_f32_e32 v133, v85
	v_add_f32_e32 v191, v191, v131
	s_waitcnt lgkmcnt(7)
	v_mfma_f32_32x32x16_bf16 v[34:49], v[178:181], v[114:117], v[34:49]
	ds_read_b128 v[220:223], v234 offset:24576
	v_exp_f32_e32 v134, v86
	v_exp_f32_e32 v135, v87
	v_add_f32_e32 v190, v190, v132
	s_waitcnt lgkmcnt(7)
	v_mfma_f32_32x32x16_bf16 v[18:33], v[182:185], v[114:117], v[18:33]
	ds_read_b128 v[224:227], v234 offset:28672
	v_exp_f32_e32 v136, v88
	v_exp_f32_e32 v137, v89
	v_add_f32_e32 v191, v191, v133
	s_waitcnt lgkmcnt(7)
	v_mfma_f32_32x32x16_bf16 v[66:81], v[186:189], v[118:121], v[66:81]
	ds_read_b128 v[166:169], v235 offset:16384
	v_exp_f32_e32 v138, v90
	v_exp_f32_e32 v139, v91
	v_cvt_pk_bf16_f32 v114, v130, v131
	s_waitcnt lgkmcnt(7)
	v_mfma_f32_32x32x16_bf16 v[50:65], v[200:203], v[118:121], v[50:65]
	ds_read_b128 v[170:173], v235 offset:20480
	v_exp_f32_e32 v140, v92
	v_exp_f32_e32 v141, v93
	v_cvt_pk_bf16_f32 v115, v132, v133
	s_waitcnt lgkmcnt(7)
	v_mfma_f32_32x32x16_bf16 v[34:49], v[204:207], v[118:121], v[34:49]
	ds_read_b128 v[178:181], v235 offset:24576
	v_exp_f32_e32 v142, v94
	v_exp_f32_e32 v143, v95
	v_add_f32_e32 v190, v190, v134
	s_waitcnt lgkmcnt(7)
	v_mfma_f32_32x32x16_bf16 v[18:33], v[208:211], v[118:121], v[18:33]
	ds_read_b128 v[182:185], v235 offset:28672
	v_exp_f32_e32 v144, v96
	v_exp_f32_e32 v145, v97
	v_add_f32_e32 v191, v191, v135
	s_waitcnt lgkmcnt(7)
	v_mfma_f32_32x32x16_bf16 v[66:81], v[212:215], v[122:125], v[66:81]
	ds_read_b128 v[186:189], v233 offset:32768
	v_exp_f32_e32 v238, v98
	v_exp_f32_e32 v239, v99
	v_cvt_pk_bf16_f32 v116, v134, v135
	s_waitcnt lgkmcnt(7)
	v_mfma_f32_32x32x16_bf16 v[50:65], v[216:219], v[122:125], v[50:65]
	ds_read_b128 v[200:203], v233 offset:36864
	v_exp_f32_e32 v240, v100
	v_exp_f32_e32 v241, v101
	v_add_f32_e32 v190, v190, v136
	s_waitcnt lgkmcnt(7)
	v_mfma_f32_32x32x16_bf16 v[34:49], v[220:223], v[122:125], v[34:49]
	ds_read_b128 v[204:207], v233 offset:40960
	v_exp_f32_e32 v242, v102
	v_exp_f32_e32 v243, v103
	v_add_f32_e32 v191, v191, v137
	s_waitcnt lgkmcnt(7)
	v_mfma_f32_32x32x16_bf16 v[18:33], v[224:227], v[122:125], v[18:33]
	ds_read_b128 v[208:211], v233 offset:45056
	v_exp_f32_e32 v244, v104
	v_exp_f32_e32 v245, v105
	v_cvt_pk_bf16_f32 v117, v136, v137
	s_waitcnt lgkmcnt(7)
	v_mfma_f32_32x32x16_bf16 v[66:81], v[166:169], v[126:129], v[66:81]
	ds_read_b128 v[166:169], v232 offset:32768
	v_exp_f32_e32 v130, v106
	v_exp_f32_e32 v131, v107
	v_add_f32_e32 v190, v190, v138
	s_waitcnt lgkmcnt(7)
	v_mfma_f32_32x32x16_bf16 v[50:65], v[170:173], v[126:129], v[50:65]
	ds_read_b128 v[170:173], v232 offset:36864
	v_exp_f32_e32 v132, v108
	v_exp_f32_e32 v133, v109
	v_add_f32_e32 v191, v191, v139
	s_waitcnt lgkmcnt(7)
	v_mfma_f32_32x32x16_bf16 v[34:49], v[178:181], v[126:129], v[34:49]
	ds_read_b128 v[178:181], v232 offset:40960
	v_exp_f32_e32 v134, v110
	v_exp_f32_e32 v135, v111
	v_add_f32_e32 v190, v190, v140
	s_waitcnt lgkmcnt(7)
	v_mfma_f32_32x32x16_bf16 v[18:33], v[182:185], v[126:129], v[18:33]
	ds_read_b128 v[182:185], v232 offset:45056
	v_exp_f32_e32 v136, v112
	v_exp_f32_e32 v137, v113
	v_add_f32_e32 v191, v191, v141
	v_cvt_pk_bf16_f32 v118, v138, v139
	v_cvt_pk_bf16_f32 v119, v140, v141
	v_add_f32_e32 v190, v190, v142
	v_add_f32_e32 v191, v191, v143
	v_cvt_pk_bf16_f32 v120, v142, v143
	v_add_f32_e32 v190, v190, v144
	v_add_f32_e32 v191, v191, v145
	v_cvt_pk_bf16_f32 v121, v144, v145
	v_add_f32_e32 v190, v190, v238
	v_add_f32_e32 v191, v191, v239
	v_cvt_pk_bf16_f32 v122, v238, v239
	v_add_f32_e32 v190, v190, v240
	v_add_f32_e32 v191, v191, v241
	v_cvt_pk_bf16_f32 v123, v240, v241
	v_add_f32_e32 v190, v190, v242
	v_add_f32_e32 v191, v191, v243
	v_cvt_pk_bf16_f32 v124, v242, v243
	v_add_f32_e32 v190, v190, v244
	v_add_f32_e32 v191, v191, v245
	v_cvt_pk_bf16_f32 v125, v244, v245
	v_add_f32_e32 v190, v190, v130
	v_add_f32_e32 v191, v191, v131
	v_cvt_pk_bf16_f32 v126, v130, v131
	v_add_f32_e32 v190, v190, v132
	v_add_f32_e32 v191, v191, v133
	v_cvt_pk_bf16_f32 v127, v132, v133
	v_add_f32_e32 v190, v190, v134
	v_add_f32_e32 v191, v191, v135
	v_cvt_pk_bf16_f32 v128, v134, v135
	v_add_f32_e32 v190, v190, v136
	v_add_f32_e32 v191, v191, v137
	v_cvt_pk_bf16_f32 v129, v136, v137
	s_waitcnt lgkmcnt(3)
	v_mfma_f32_32x32x16_bf16 v[66:81], v[166:169], v[114:117], v[66:81]
	ds_read_b128 v[212:215], v234 offset:32768
	s_waitcnt lgkmcnt(3)
	v_mfma_f32_32x32x16_bf16 v[50:65], v[170:173], v[114:117], v[50:65]
	ds_read_b128 v[216:219], v234 offset:36864
	s_waitcnt lgkmcnt(3)
	v_mfma_f32_32x32x16_bf16 v[34:49], v[178:181], v[114:117], v[34:49]
	ds_read_b128 v[220:223], v234 offset:40960
	s_waitcnt lgkmcnt(3)
	v_mfma_f32_32x32x16_bf16 v[18:33], v[182:185], v[114:117], v[18:33]
	ds_read_b128 v[224:227], v234 offset:45056
	s_waitcnt lgkmcnt(11)
	v_mfma_f32_32x32x16_bf16 v[66:81], v[186:189], v[118:121], v[66:81]
	ds_read_b128 v[166:169], v235 offset:32768
	s_waitcnt lgkmcnt(11)
	v_mfma_f32_32x32x16_bf16 v[50:65], v[200:203], v[118:121], v[50:65]
	ds_read_b128 v[170:173], v235 offset:36864
	s_waitcnt lgkmcnt(11)
	v_mfma_f32_32x32x16_bf16 v[34:49], v[204:207], v[118:121], v[34:49]
	ds_read_b128 v[178:181], v235 offset:40960
	s_waitcnt lgkmcnt(11)
	v_mfma_f32_32x32x16_bf16 v[18:33], v[208:211], v[118:121], v[18:33]
	ds_read_b128 v[182:185], v235 offset:45056
	s_waitcnt lgkmcnt(7)
	v_mfma_f32_32x32x16_bf16 v[66:81], v[212:215], v[122:125], v[66:81]
	s_waitcnt lgkmcnt(6)
	v_mfma_f32_32x32x16_bf16 v[50:65], v[216:219], v[122:125], v[50:65]
	s_waitcnt lgkmcnt(5)
	v_mfma_f32_32x32x16_bf16 v[34:49], v[220:223], v[122:125], v[34:49]
	s_waitcnt lgkmcnt(4)
	v_mfma_f32_32x32x16_bf16 v[18:33], v[224:227], v[122:125], v[18:33]
	s_waitcnt lgkmcnt(3)
	v_mfma_f32_32x32x16_bf16 v[66:81], v[166:169], v[126:129], v[66:81]
	s_waitcnt lgkmcnt(2)
	v_mfma_f32_32x32x16_bf16 v[50:65], v[170:173], v[126:129], v[50:65]
	s_waitcnt lgkmcnt(1)
	v_mfma_f32_32x32x16_bf16 v[34:49], v[178:181], v[126:129], v[34:49]
	s_waitcnt lgkmcnt(0)
	v_mfma_f32_32x32x16_bf16 v[18:33], v[182:185], v[126:129], v[18:33]
	v_add_f32_e32 v98, v190, v191
	v_and_b32_e32 v178, 63, v163
	v_bfe_u32 v252, v163, 5, 1
	v_lshlrev_b32_e32 v164, 3, v252
	s_waitcnt lgkmcnt(0)
	s_barrier
; template <int MODE> __device__ __forceinline__ void diff_attn_item(const bf16* __restrict__ Qb, const bf16* __restrict__ Kh, const bf16* __restrict__ Vh, ...
;     ...
;   lsum += __shfl_xor(lsum, 32);
;   const float rl = 1.f / lsum;
;   float* E = (float*)lds;
;   if (map == 1) {
	v_and_b32_e32 v83, 64, v193
	v_xor_b32_e32 v82, 32, v193
	v_add_u32_e32 v83, 64, v83
	v_cmp_lt_i32_e32 vcc, v82, v83
	s_nop 1
	v_cndmask_b32_e32 v82, v193, v82, vcc
	v_lshlrev_b32_e32 v83, 2, v82
	ds_bpermute_b32 v82, v83, v98
	s_nop 0
	s_waitcnt lgkmcnt(0)
	v_add_f32_e32 v82, v98, v82
	v_div_scale_f32 v84, s[4:5], v82, v82, 1.0
	v_rcp_f32_e32 v85, v84
	s_nop 0
	v_fma_f32 v98, -v84, v85, 1.0
	v_fmac_f32_e32 v85, v98, v85
	v_div_scale_f32 v98, vcc, 1.0, v82, 1.0
	s_nop 0
	v_mul_f32_e32 v90, v98, v85
	v_fma_f32 v91, -v84, v90, v98
	v_fmac_f32_e32 v90, v91, v85
	v_fma_f32 v84, -v84, v90, v98
	v_div_fmas_f32 v84, v84, v85, v90
	v_div_fixup_f32 v82, v84, v82, 1.0
	v_cmp_eq_u32_e32 vcc, 1, v177
	s_nop 0
	s_branch .Lda1_join
